# phase 4 carry scan unrolled with a 32-load ring (loads four blocks ahead of the serial recurrence)
# baseline (speedup 1.0000x reference)
; DEV unsigned pk_bf16(float lo, float hi) { unsigned r; asm("v_cvt_pk_bf16_f32 %0, %1, %2" : "=v"(r) : "v"(lo), "v"(hi)); return r; }
; DEV float bflo(unsigned w) { return __uint_as_float(w << 16); }
; DEV float bfhi(unsigned w) { return __uint_as_float(w & 0xffff0000u); }
; DEV Disc s5_disc(const P& p, int l, int dir, int g, int pp) {
;   Disc d; const int gi = (l * 2 + dir) * 32 + g;
;   d.dt = (double)expf(p.log_dt[gi]); d.are = p.a_re[gi * 64 + pp]; d.aim = p.a_im[gi * 64 + pp];
;   const float mag = __expf((float)(d.dt * (double)d.are)); float sn, cs; sincos_d(d.dt * (double)d.aim, sn, cs);
;   const float abr = mag * cs, abi = mag * sn, den = d.are * d.are + d.aim * d.aim, nr = abr - 1.0f, ni = abi;
;   d.fre = (nr * d.are + ni * d.aim) / den; d.fim = (ni * d.are - nr * d.aim) / den;
;   return d;
; }
; DEV float2 cpow(const Disc& d, int e) {
;   const float mag = __expf((float)((double)e * d.dt * (double)d.are)); float sn, cs; sincos_d((double)e * d.dt * (double)d.aim, sn, cs);
;   return make_float2(mag * cs, mag * sn);
; DEV void ph_carry(const P& p, int l, bool need) {
;     ...
;     const int idx = it * 256 + tid, pp = idx & 63, dir = (idx >> 6) & 1, g = (idx >> 7) & 31, b = idx >> 12;
;     const Disc d = s5_disc(p, l, dir, g, pp);
;     const float2 at = cpow(d, 32);
;     unsigned* S = (unsigned*)(p.ws + OFF_S) + (g * 256 + dir * 128 + pp * 2) / 2;
;     float sr = 0.f, si = 0.f;
;     for (int blk = 0; blk < 17; ++blk) {
;       unsigned v[8]; int rows[8];
; #pragma unroll
;       for (int e = 0; e < 8; ++e) {
;         int r;
;         if (blk == 0) r = 1024 + b * 8 + (dir ? 7 - e : e);
;         else { const int j = (blk - 1) * 8 + e; r = b * 128 + (dir ? 127 - j : j); }
;         rows[e] = r; v[e] = S[(size_t)r * 4096];
;       }
; #pragma unroll
;       for (int e = 0; e < 8; ++e) {
;         S[(size_t)rows[e] * 4096] = pk_bf16(sr, si);
;         const float nr = at.x * sr - at.y * si + bflo(v[e]), ni = at.x * si + at.y * sr + bfhi(v[e]);
;         sr = nr; si = ni;
;       }
.LBB0_305:
	v_lshl_add_u32 v0, s10, 8, v24
	v_bfe_u32 v4, v0, 7, 5
	v_or_b32_e32 v40, v4, v25
	v_ashrrev_i32_e32 v14, 12, v0
	v_lshl_add_u64 v[0:1], v[40:41], 2, s[6:7]
	global_load_dword v35, v[0:1], off
	v_lshlrev_b32_e32 v6, 3, v14
	v_lshl_or_b32 v40, v40, 6, v22
	v_add_u32_e32 v15, 0x400, v6
	v_lshlrev_b64 v[0:1], 2, v[40:41]
	v_lshl_or_b32 v40, v4, 9, v33
	v_or_b32_e32 v4, v15, v27
	v_lshl_add_u64 v[2:3], s[40:41], 0, v[0:1]
	v_lshl_add_u64 v[0:1], s[42:43], 0, v[0:1]
	v_ashrrev_i32_e32 v5, 31, v4
	global_load_dword v36, v[2:3], off
	global_load_dword v37, v[0:1], off
	v_lshl_add_u64 v[0:1], s[8:9], 0, v[40:41]
	v_or_b32_e32 v2, v15, v26
	v_lshlrev_b64 v[4:5], 14, v[4:5]
	v_ashrrev_i32_e32 v3, 31, v2
	v_lshl_add_u64 v[12:13], v[0:1], 0, v[4:5]
	v_or_b32_e32 v4, v15, v28
	v_lshlrev_b64 v[2:3], 14, v[2:3]
	v_ashrrev_i32_e32 v5, 31, v4
	v_lshl_add_u64 v[2:3], v[0:1], 0, v[2:3]
	v_lshlrev_b64 v[4:5], 14, v[4:5]
	v_lshl_add_u64 v[8:9], v[0:1], 0, v[4:5]
	global_load_dword v38, v[2:3], off
	global_load_dword v39, v[12:13], off
	global_load_dword v40, v[8:9], off
	v_or_b32_e32 v4, v15, v29
	v_ashrrev_i32_e32 v5, 31, v4
	v_lshlrev_b64 v[4:5], 14, v[4:5]
	v_lshl_add_u64 v[10:11], v[0:1], 0, v[4:5]
	v_sub_u32_e32 v4, v6, v23
	v_ashrrev_i32_e32 v5, 31, v4
	v_lshlrev_b64 v[4:5], 14, v[4:5]
	v_lshl_add_u64 v[4:5], v[0:1], 0, v[4:5]
	s_mov_b32 s2, 0x1010000
	global_load_dword v43, v[10:11], off
	v_add_co_u32_e64 v6, s[38:39], s2, v4
	v_or_b32_e32 v4, v15, v30
	s_nop 0
	v_addc_co_u32_e64 v7, s[38:39], 0, v5, s[38:39]
	v_ashrrev_i32_e32 v5, 31, v4
	v_lshlrev_b64 v[4:5], 14, v[4:5]
	v_lshl_add_u64 v[18:19], v[0:1], 0, v[4:5]
	global_load_dword v49, v[18:19], off
	global_load_dword v48, v[6:7], off
	v_lshlrev_b32_e32 v34, 7, v14
	v_or_b32_e32 v14, v15, v31
	v_or_b32_e32 v16, v15, v32
	v_ashrrev_i32_e32 v15, 31, v14
	v_ashrrev_i32_e32 v17, 31, v16
	v_lshlrev_b64 v[14:15], 14, v[14:15]
	v_lshlrev_b64 v[20:21], 14, v[16:17]
	v_lshl_add_u64 v[16:17], v[0:1], 0, v[14:15]
	v_lshl_add_u64 v[14:15], v[0:1], 0, v[20:21]
	global_load_dword v50, v[16:17], off
	global_load_dword v51, v[14:15], off
	v_cvt_pk_bf16_f32 v42, v41, v41
	global_store_dword v[2:3], v42, off
	s_mov_b32 s2, 7
	s_movk_i32 s3, 0x78
	s_waitcnt vmcnt(11)
	v_mul_f32_e32 v2, 0x3fb8aa3b, v35
	v_fma_f32 v20, v35, s34, -v2
	v_rndne_f32_e32 v3, v2
	v_fmac_f32_e32 v20, 0x32a5705f, v35
	v_sub_f32_e32 v21, v2, v3
	v_add_f32_e32 v20, v21, v20
	v_cvt_i32_f32_e32 v44, v3
	v_exp_f32_e32 v45, v20
	v_cmp_ngt_f32_e64 s[38:39], s35, v35
	s_waitcnt vmcnt(10)
	v_cvt_f64_f32_e32 v[4:5], v36
	s_waitcnt vmcnt(9)
	v_cvt_f64_f32_e32 v[2:3], v37
	s_waitcnt vmcnt(8)
	v_lshlrev_b32_e32 v20, 16, v38
	v_and_b32_e32 v21, 0xffff0000, v38
	s_waitcnt vmcnt(7)
	v_lshlrev_b32_e32 v36, 16, v39
	v_and_b32_e32 v37, 0xffff0000, v39
	s_waitcnt vmcnt(6)
	v_lshlrev_b32_e32 v38, 16, v40
	v_and_b32_e32 v39, 0xffff0000, v40
	v_ldexp_f32 v40, v45, v44
	v_cndmask_b32_e64 v40, 0, v40, s[38:39]
	v_cmp_nlt_f32_e64 s[38:39], s36, v35
	s_waitcnt vmcnt(5)
	v_lshlrev_b32_e32 v42, 16, v43
	v_cndmask_b32_e64 v35, v236, v40, s[38:39]
	v_cvt_f64_f32_e32 v[44:45], v35
	v_ldexp_f64 v[44:45], v[44:45], 5
	v_mul_f64 v[4:5], v[44:45], v[4:5]
	v_mul_f64 v[2:3], v[44:45], v[2:3]
	v_cvt_f32_f64_e32 v35, v[4:5]
	v_mul_f64 v[4:5], v[2:3], s[28:29]
	v_rndne_f64_e32 v[4:5], v[4:5]
	v_fmac_f64_e32 v[2:3], s[30:31], v[4:5]
	v_mul_f64 v[2:3], v[2:3], s[28:29]
	v_mul_f32_e32 v35, 0x3fb8aa3b, v35
	v_cvt_f32_f64_e32 v2, v[2:3]
	v_exp_f32_e32 v35, v35
	v_cos_f32_e32 v3, v2
	v_sin_f32_e32 v4, v2
	v_and_b32_e32 v43, 0xffff0000, v43
	s_waitcnt vmcnt(3)
	v_lshlrev_b32_e32 v44, 16, v48
	v_mul_f32_e32 v2, v35, v3
	v_mul_f32_e32 v4, v35, v4
	v_mul_f32_e32 v5, 0, v2
	v_mul_f32_e32 v47, 0, v4
	v_sub_f32_e32 v46, v5, v47
	v_fmac_f32_e32 v47, 0, v2
	v_pk_add_f32 v[20:21], v[46:47], v[20:21]
	v_mov_b32_e32 v3, v2
	v_cvt_pk_bf16_f32 v5, v20, v21
	global_store_dword v[12:13], v5, off
	v_mov_b32_e32 v5, v4
	v_pk_mul_f32 v[12:13], v[4:5], v[20:21] op_sel_hi:[0,1]
	v_pk_fma_f32 v[46:47], v[2:3], v[20:21], v[12:13] op_sel:[0,0,1] op_sel_hi:[1,1,0] neg_lo:[0,0,1] neg_hi:[0,0,1]
	v_pk_fma_f32 v[12:13], v[2:3], v[20:21], v[12:13] op_sel:[0,0,1] op_sel_hi:[0,1,0]
	v_mov_b32_e32 v47, v13
	v_pk_add_f32 v[12:13], v[46:47], v[36:37]
	v_and_b32_e32 v45, 0xffff0000, v48
	v_cvt_pk_bf16_f32 v20, v12, v13
	global_store_dword v[8:9], v20, off
	v_pk_mul_f32 v[8:9], v[4:5], v[12:13] op_sel_hi:[0,1]
	v_pk_fma_f32 v[20:21], v[2:3], v[12:13], v[8:9] op_sel:[0,0,1] op_sel_hi:[1,1,0] neg_lo:[0,0,1] neg_hi:[0,0,1]
	v_pk_fma_f32 v[8:9], v[2:3], v[12:13], v[8:9] op_sel:[0,0,1] op_sel_hi:[0,1,0]
	v_mov_b32_e32 v21, v9
	v_pk_add_f32 v[8:9], v[20:21], v[38:39]
	s_nop 0
	v_cvt_pk_bf16_f32 v12, v8, v9
	global_store_dword v[10:11], v12, off
	v_pk_mul_f32 v[10:11], v[4:5], v[8:9] op_sel_hi:[0,1]
	v_pk_fma_f32 v[12:13], v[2:3], v[8:9], v[10:11] op_sel:[0,0,1] op_sel_hi:[1,1,0] neg_lo:[0,0,1] neg_hi:[0,0,1]
	v_pk_fma_f32 v[8:9], v[2:3], v[8:9], v[10:11] op_sel:[0,0,1] op_sel_hi:[0,1,0]
	v_mov_b32_e32 v13, v9
	v_pk_add_f32 v[8:9], v[12:13], v[42:43]
	s_waitcnt vmcnt(4)
; DEV unsigned pk_bf16(float lo, float hi) { unsigned r; asm("v_cvt_pk_bf16_f32 %0, %1, %2" : "=v"(r) : "v"(lo), "v"(hi)); return r; }
; DEV float bflo(unsigned w) { return __uint_as_float(w << 16); }
; DEV float bfhi(unsigned w) { return __uint_as_float(w & 0xffff0000u); }
; DEV void ph_carry(const P& p, int l, bool need) {
;     ...
;     for (int blk = 0; blk < 17; ++blk) {
;       unsigned v[8]; int rows[8];
; #pragma unroll
;       for (int e = 0; e < 8; ++e) {
;         int r;
;         if (blk == 0) r = 1024 + b * 8 + (dir ? 7 - e : e);
;         else { const int j = (blk - 1) * 8 + e; r = b * 128 + (dir ? 127 - j : j); }
;         rows[e] = r; v[e] = S[(size_t)r * 4096];
;       }
; #pragma unroll
;       for (int e = 0; e < 8; ++e) {
;         S[(size_t)rows[e] * 4096] = pk_bf16(sr, si);
;         const float nr = at.x * sr - at.y * si + bflo(v[e]), ni = at.x * si + at.y * sr + bfhi(v[e]);
;         sr = nr; si = ni;
;       }
	v_and_b32_e32 v13, 0xffff0000, v51
	v_cvt_pk_bf16_f32 v10, v8, v9
	global_store_dword v[6:7], v10, off
	v_pk_mul_f32 v[6:7], v[4:5], v[8:9] op_sel_hi:[0,1]
	v_pk_fma_f32 v[10:11], v[2:3], v[8:9], v[6:7] op_sel:[0,0,1] op_sel_hi:[1,1,0] neg_lo:[0,0,1] neg_hi:[0,0,1]
	v_pk_fma_f32 v[6:7], v[2:3], v[8:9], v[6:7] op_sel:[0,0,1] op_sel_hi:[0,1,0]
	v_mov_b32_e32 v11, v7
	v_pk_add_f32 v[10:11], v[10:11], v[44:45]
	v_lshlrev_b32_e32 v6, 16, v49
	v_cvt_pk_bf16_f32 v20, v10, v11
	global_store_dword v[18:19], v20, off
	v_pk_mul_f32 v[18:19], v[4:5], v[10:11] op_sel_hi:[0,1]
	v_pk_fma_f32 v[20:21], v[2:3], v[10:11], v[18:19] op_sel:[0,0,1] op_sel_hi:[1,1,0] neg_lo:[0,0,1] neg_hi:[0,0,1]
	v_pk_fma_f32 v[10:11], v[2:3], v[10:11], v[18:19] op_sel:[0,0,1] op_sel_hi:[0,1,0]
	v_and_b32_e32 v7, 0xffff0000, v49
	v_mov_b32_e32 v21, v11
	v_pk_add_f32 v[6:7], v[20:21], v[6:7]
	v_lshlrev_b32_e32 v8, 16, v50
	v_cvt_pk_bf16_f32 v10, v6, v7
	global_store_dword v[16:17], v10, off
	v_pk_mul_f32 v[10:11], v[4:5], v[6:7] op_sel_hi:[0,1]
	v_pk_fma_f32 v[16:17], v[2:3], v[6:7], v[10:11] op_sel:[0,0,1] op_sel_hi:[1,1,0] neg_lo:[0,0,1] neg_hi:[0,0,1]
	v_pk_fma_f32 v[6:7], v[2:3], v[6:7], v[10:11] op_sel:[0,0,1] op_sel_hi:[0,1,0]
	v_and_b32_e32 v9, 0xffff0000, v50
	v_mov_b32_e32 v17, v7
	v_pk_add_f32 v[6:7], v[16:17], v[8:9]
	v_lshlrev_b32_e32 v12, 16, v51
	v_cvt_pk_bf16_f32 v8, v6, v7
	global_store_dword v[14:15], v8, off
	v_pk_mul_f32 v[8:9], v[4:5], v[6:7] op_sel_hi:[0,1]
	v_pk_fma_f32 v[10:11], v[2:3], v[6:7], v[8:9] op_sel:[0,0,1] op_sel_hi:[1,1,0] neg_lo:[0,0,1] neg_hi:[0,0,1]
	v_pk_fma_f32 v[6:7], v[2:3], v[6:7], v[8:9] op_sel:[0,0,1] op_sel_hi:[0,1,0]
	v_mov_b32_e32 v11, v7
	v_pk_add_f32 v[6:7], v[10:11], v[12:13]
	v_mov_b32_e32 v88, 0x4000
	v_mov_b32_e32 v89, 0
	v_mov_b32_e32 v90, 0xffffc000
	v_mov_b32_e32 v91, -1
	v_mov_b32_e32 v92, 0x7f
	v_cndmask_b32_e32 v88, v90, v88, vcc
	v_cndmask_b32_e32 v89, v91, v89, vcc
	v_cndmask_b32_e32 v92, v92, v41, vcc
	v_add_u32_e32 v92, v92, v34
	v_ashrrev_i32_e32 v93, 31, v92
	v_lshlrev_b64 v[92:93], 14, v[92:93]
	v_lshl_add_u64 v[84:85], v[0:1], 0, v[92:93]
	v_lshl_add_u64 v[86:87], v[0:1], 0, v[92:93]
	global_load_dword v52, v[84:85], off
	v_lshl_add_u64 v[84:85], v[84:85], 0, v[88:89]
	global_load_dword v53, v[84:85], off
	v_lshl_add_u64 v[84:85], v[84:85], 0, v[88:89]
	global_load_dword v54, v[84:85], off
	v_lshl_add_u64 v[84:85], v[84:85], 0, v[88:89]
	global_load_dword v55, v[84:85], off
	v_lshl_add_u64 v[84:85], v[84:85], 0, v[88:89]
	global_load_dword v56, v[84:85], off
	v_lshl_add_u64 v[84:85], v[84:85], 0, v[88:89]
	global_load_dword v57, v[84:85], off
	v_lshl_add_u64 v[84:85], v[84:85], 0, v[88:89]
	global_load_dword v58, v[84:85], off
	v_lshl_add_u64 v[84:85], v[84:85], 0, v[88:89]
	global_load_dword v59, v[84:85], off
	v_lshl_add_u64 v[84:85], v[84:85], 0, v[88:89]
	global_load_dword v60, v[84:85], off
	v_lshl_add_u64 v[84:85], v[84:85], 0, v[88:89]
	global_load_dword v61, v[84:85], off
	v_lshl_add_u64 v[84:85], v[84:85], 0, v[88:89]
	global_load_dword v62, v[84:85], off
	v_lshl_add_u64 v[84:85], v[84:85], 0, v[88:89]
	global_load_dword v63, v[84:85], off
	v_lshl_add_u64 v[84:85], v[84:85], 0, v[88:89]
	global_load_dword v64, v[84:85], off
	v_lshl_add_u64 v[84:85], v[84:85], 0, v[88:89]
	global_load_dword v65, v[84:85], off
	v_lshl_add_u64 v[84:85], v[84:85], 0, v[88:89]
	global_load_dword v66, v[84:85], off
	v_lshl_add_u64 v[84:85], v[84:85], 0, v[88:89]
	global_load_dword v67, v[84:85], off
	v_lshl_add_u64 v[84:85], v[84:85], 0, v[88:89]
	global_load_dword v68, v[84:85], off
	v_lshl_add_u64 v[84:85], v[84:85], 0, v[88:89]
	global_load_dword v69, v[84:85], off
	v_lshl_add_u64 v[84:85], v[84:85], 0, v[88:89]
	global_load_dword v70, v[84:85], off
	v_lshl_add_u64 v[84:85], v[84:85], 0, v[88:89]
	global_load_dword v71, v[84:85], off
	v_lshl_add_u64 v[84:85], v[84:85], 0, v[88:89]
	global_load_dword v72, v[84:85], off
	v_lshl_add_u64 v[84:85], v[84:85], 0, v[88:89]
	global_load_dword v73, v[84:85], off
	v_lshl_add_u64 v[84:85], v[84:85], 0, v[88:89]
	global_load_dword v74, v[84:85], off
	v_lshl_add_u64 v[84:85], v[84:85], 0, v[88:89]
	global_load_dword v75, v[84:85], off
	v_lshl_add_u64 v[84:85], v[84:85], 0, v[88:89]
	global_load_dword v76, v[84:85], off
	v_lshl_add_u64 v[84:85], v[84:85], 0, v[88:89]
	global_load_dword v77, v[84:85], off
	v_lshl_add_u64 v[84:85], v[84:85], 0, v[88:89]
	global_load_dword v78, v[84:85], off
	v_lshl_add_u64 v[84:85], v[84:85], 0, v[88:89]
	global_load_dword v79, v[84:85], off
	v_lshl_add_u64 v[84:85], v[84:85], 0, v[88:89]
	global_load_dword v80, v[84:85], off
	v_lshl_add_u64 v[84:85], v[84:85], 0, v[88:89]
	global_load_dword v81, v[84:85], off
	v_lshl_add_u64 v[84:85], v[84:85], 0, v[88:89]
	global_load_dword v82, v[84:85], off
	v_lshl_add_u64 v[84:85], v[84:85], 0, v[88:89]
	global_load_dword v83, v[84:85], off
	v_lshl_add_u64 v[84:85], v[84:85], 0, v[88:89]
	v_cvt_pk_bf16_f32 v46, v6, v7
	global_store_dword v[86:87], v46, off
	v_pk_mul_f32 v[42:43], v[4:5], v[6:7]
	v_lshl_add_u64 v[86:87], v[86:87], 0, v[88:89]
	v_pk_fma_f32 v[44:45], v[2:3], v[6:7], v[42:43] op_sel:[0,0,1] op_sel_hi:[1,1,0] neg_lo:[0,0,1] neg_hi:[0,0,1]
	v_pk_fma_f32 v[6:7], v[2:3], v[6:7], v[42:43] op_sel:[0,0,1] op_sel_hi:[1,1,0]
	s_waitcnt vmcnt(32)
	v_lshlrev_b32_e32 v8, 16, v52
	v_and_b32_e32 v9, 0xffff0000, v52
	v_mov_b32_e32 v45, v7
	v_pk_add_f32 v[6:7], v[44:45], v[8:9]
	v_cvt_pk_bf16_f32 v47, v6, v7
	global_store_dword v[86:87], v47, off
	v_pk_mul_f32 v[42:43], v[4:5], v[6:7]
	v_lshl_add_u64 v[86:87], v[86:87], 0, v[88:89]
	v_pk_fma_f32 v[44:45], v[2:3], v[6:7], v[42:43] op_sel:[0,0,1] op_sel_hi:[1,1,0] neg_lo:[0,0,1] neg_hi:[0,0,1]
	v_pk_fma_f32 v[6:7], v[2:3], v[6:7], v[42:43] op_sel:[0,0,1] op_sel_hi:[1,1,0]
	s_waitcnt vmcnt(32)
; DEV unsigned pk_bf16(float lo, float hi) { unsigned r; asm("v_cvt_pk_bf16_f32 %0, %1, %2" : "=v"(r) : "v"(lo), "v"(hi)); return r; }
; DEV float bflo(unsigned w) { return __uint_as_float(w << 16); }
; DEV float bfhi(unsigned w) { return __uint_as_float(w & 0xffff0000u); }
; DEV void ph_carry(const P& p, int l, bool need) {
;     ...
;     for (int blk = 0; blk < 17; ++blk) {
;       unsigned v[8]; int rows[8];
; #pragma unroll
;       for (int e = 0; e < 8; ++e) {
;         int r;
;         if (blk == 0) r = 1024 + b * 8 + (dir ? 7 - e : e);
;         else { const int j = (blk - 1) * 8 + e; r = b * 128 + (dir ? 127 - j : j); }
;         rows[e] = r; v[e] = S[(size_t)r * 4096];
;       }
; #pragma unroll
;       for (int e = 0; e < 8; ++e) {
;         S[(size_t)rows[e] * 4096] = pk_bf16(sr, si);
;         const float nr = at.x * sr - at.y * si + bflo(v[e]), ni = at.x * si + at.y * sr + bfhi(v[e]);
;         sr = nr; si = ni;
;       }
	v_lshlrev_b32_e32 v8, 16, v53
	v_and_b32_e32 v9, 0xffff0000, v53
	v_mov_b32_e32 v45, v7
	v_pk_add_f32 v[6:7], v[44:45], v[8:9]
	v_cvt_pk_bf16_f32 v46, v6, v7
	global_store_dword v[86:87], v46, off
	v_pk_mul_f32 v[42:43], v[4:5], v[6:7]
	v_lshl_add_u64 v[86:87], v[86:87], 0, v[88:89]
	v_pk_fma_f32 v[44:45], v[2:3], v[6:7], v[42:43] op_sel:[0,0,1] op_sel_hi:[1,1,0] neg_lo:[0,0,1] neg_hi:[0,0,1]
	v_pk_fma_f32 v[6:7], v[2:3], v[6:7], v[42:43] op_sel:[0,0,1] op_sel_hi:[1,1,0]
	s_waitcnt vmcnt(32)
	v_lshlrev_b32_e32 v8, 16, v54
	v_and_b32_e32 v9, 0xffff0000, v54
	v_mov_b32_e32 v45, v7
	v_pk_add_f32 v[6:7], v[44:45], v[8:9]
	v_cvt_pk_bf16_f32 v47, v6, v7
	global_store_dword v[86:87], v47, off
	v_pk_mul_f32 v[42:43], v[4:5], v[6:7]
	v_lshl_add_u64 v[86:87], v[86:87], 0, v[88:89]
	v_pk_fma_f32 v[44:45], v[2:3], v[6:7], v[42:43] op_sel:[0,0,1] op_sel_hi:[1,1,0] neg_lo:[0,0,1] neg_hi:[0,0,1]
	v_pk_fma_f32 v[6:7], v[2:3], v[6:7], v[42:43] op_sel:[0,0,1] op_sel_hi:[1,1,0]
	s_waitcnt vmcnt(32)
	v_lshlrev_b32_e32 v8, 16, v55
	v_and_b32_e32 v9, 0xffff0000, v55
	v_mov_b32_e32 v45, v7
	v_pk_add_f32 v[6:7], v[44:45], v[8:9]
	v_cvt_pk_bf16_f32 v46, v6, v7
	global_store_dword v[86:87], v46, off
	v_pk_mul_f32 v[42:43], v[4:5], v[6:7]
	v_lshl_add_u64 v[86:87], v[86:87], 0, v[88:89]
	v_pk_fma_f32 v[44:45], v[2:3], v[6:7], v[42:43] op_sel:[0,0,1] op_sel_hi:[1,1,0] neg_lo:[0,0,1] neg_hi:[0,0,1]
	v_pk_fma_f32 v[6:7], v[2:3], v[6:7], v[42:43] op_sel:[0,0,1] op_sel_hi:[1,1,0]
	s_waitcnt vmcnt(32)
	v_lshlrev_b32_e32 v8, 16, v56
	v_and_b32_e32 v9, 0xffff0000, v56
	v_mov_b32_e32 v45, v7
	v_pk_add_f32 v[6:7], v[44:45], v[8:9]
	v_cvt_pk_bf16_f32 v47, v6, v7
	global_store_dword v[86:87], v47, off
	v_pk_mul_f32 v[42:43], v[4:5], v[6:7]
	v_lshl_add_u64 v[86:87], v[86:87], 0, v[88:89]
	v_pk_fma_f32 v[44:45], v[2:3], v[6:7], v[42:43] op_sel:[0,0,1] op_sel_hi:[1,1,0] neg_lo:[0,0,1] neg_hi:[0,0,1]
	v_pk_fma_f32 v[6:7], v[2:3], v[6:7], v[42:43] op_sel:[0,0,1] op_sel_hi:[1,1,0]
	s_waitcnt vmcnt(32)
	v_lshlrev_b32_e32 v8, 16, v57
	v_and_b32_e32 v9, 0xffff0000, v57
	v_mov_b32_e32 v45, v7
	v_pk_add_f32 v[6:7], v[44:45], v[8:9]
	v_cvt_pk_bf16_f32 v46, v6, v7
	global_store_dword v[86:87], v46, off
	v_pk_mul_f32 v[42:43], v[4:5], v[6:7]
	v_lshl_add_u64 v[86:87], v[86:87], 0, v[88:89]
	v_pk_fma_f32 v[44:45], v[2:3], v[6:7], v[42:43] op_sel:[0,0,1] op_sel_hi:[1,1,0] neg_lo:[0,0,1] neg_hi:[0,0,1]
	v_pk_fma_f32 v[6:7], v[2:3], v[6:7], v[42:43] op_sel:[0,0,1] op_sel_hi:[1,1,0]
	s_waitcnt vmcnt(32)
	v_lshlrev_b32_e32 v8, 16, v58
	v_and_b32_e32 v9, 0xffff0000, v58
	v_mov_b32_e32 v45, v7
	v_pk_add_f32 v[6:7], v[44:45], v[8:9]
	v_cvt_pk_bf16_f32 v47, v6, v7
	global_store_dword v[86:87], v47, off
	v_pk_mul_f32 v[42:43], v[4:5], v[6:7]
	v_lshl_add_u64 v[86:87], v[86:87], 0, v[88:89]
	v_pk_fma_f32 v[44:45], v[2:3], v[6:7], v[42:43] op_sel:[0,0,1] op_sel_hi:[1,1,0] neg_lo:[0,0,1] neg_hi:[0,0,1]
	v_pk_fma_f32 v[6:7], v[2:3], v[6:7], v[42:43] op_sel:[0,0,1] op_sel_hi:[1,1,0]
	s_waitcnt vmcnt(32)
	v_lshlrev_b32_e32 v8, 16, v59
	v_and_b32_e32 v9, 0xffff0000, v59
	v_mov_b32_e32 v45, v7
	v_pk_add_f32 v[6:7], v[44:45], v[8:9]
	global_load_dword v52, v[84:85], off
	v_lshl_add_u64 v[84:85], v[84:85], 0, v[88:89]
	global_load_dword v53, v[84:85], off
	v_lshl_add_u64 v[84:85], v[84:85], 0, v[88:89]
	global_load_dword v54, v[84:85], off
	v_lshl_add_u64 v[84:85], v[84:85], 0, v[88:89]
	global_load_dword v55, v[84:85], off
	v_lshl_add_u64 v[84:85], v[84:85], 0, v[88:89]
	global_load_dword v56, v[84:85], off
	v_lshl_add_u64 v[84:85], v[84:85], 0, v[88:89]
	global_load_dword v57, v[84:85], off
	v_lshl_add_u64 v[84:85], v[84:85], 0, v[88:89]
	global_load_dword v58, v[84:85], off
	v_lshl_add_u64 v[84:85], v[84:85], 0, v[88:89]
	global_load_dword v59, v[84:85], off
	v_lshl_add_u64 v[84:85], v[84:85], 0, v[88:89]
	v_cvt_pk_bf16_f32 v46, v6, v7
	global_store_dword v[86:87], v46, off
	v_pk_mul_f32 v[42:43], v[4:5], v[6:7]
	v_lshl_add_u64 v[86:87], v[86:87], 0, v[88:89]
	v_pk_fma_f32 v[44:45], v[2:3], v[6:7], v[42:43] op_sel:[0,0,1] op_sel_hi:[1,1,0] neg_lo:[0,0,1] neg_hi:[0,0,1]
	v_pk_fma_f32 v[6:7], v[2:3], v[6:7], v[42:43] op_sel:[0,0,1] op_sel_hi:[1,1,0]
	s_waitcnt vmcnt(40)
	v_lshlrev_b32_e32 v8, 16, v60
	v_and_b32_e32 v9, 0xffff0000, v60
	v_mov_b32_e32 v45, v7
	v_pk_add_f32 v[6:7], v[44:45], v[8:9]
	v_cvt_pk_bf16_f32 v47, v6, v7
	global_store_dword v[86:87], v47, off
	v_pk_mul_f32 v[42:43], v[4:5], v[6:7]
	v_lshl_add_u64 v[86:87], v[86:87], 0, v[88:89]
	v_pk_fma_f32 v[44:45], v[2:3], v[6:7], v[42:43] op_sel:[0,0,1] op_sel_hi:[1,1,0] neg_lo:[0,0,1] neg_hi:[0,0,1]
	v_pk_fma_f32 v[6:7], v[2:3], v[6:7], v[42:43] op_sel:[0,0,1] op_sel_hi:[1,1,0]
	s_waitcnt vmcnt(40)
	v_lshlrev_b32_e32 v8, 16, v61
	v_and_b32_e32 v9, 0xffff0000, v61
	v_mov_b32_e32 v45, v7
	v_pk_add_f32 v[6:7], v[44:45], v[8:9]
	v_cvt_pk_bf16_f32 v46, v6, v7
	global_store_dword v[86:87], v46, off
	v_pk_mul_f32 v[42:43], v[4:5], v[6:7]
	v_lshl_add_u64 v[86:87], v[86:87], 0, v[88:89]
	v_pk_fma_f32 v[44:45], v[2:3], v[6:7], v[42:43] op_sel:[0,0,1] op_sel_hi:[1,1,0] neg_lo:[0,0,1] neg_hi:[0,0,1]
	v_pk_fma_f32 v[6:7], v[2:3], v[6:7], v[42:43] op_sel:[0,0,1] op_sel_hi:[1,1,0]
	s_waitcnt vmcnt(40)
	v_lshlrev_b32_e32 v8, 16, v62
	v_and_b32_e32 v9, 0xffff0000, v62
	v_mov_b32_e32 v45, v7
	v_pk_add_f32 v[6:7], v[44:45], v[8:9]
	v_cvt_pk_bf16_f32 v47, v6, v7
	global_store_dword v[86:87], v47, off
	v_pk_mul_f32 v[42:43], v[4:5], v[6:7]
	v_lshl_add_u64 v[86:87], v[86:87], 0, v[88:89]
	v_pk_fma_f32 v[44:45], v[2:3], v[6:7], v[42:43] op_sel:[0,0,1] op_sel_hi:[1,1,0] neg_lo:[0,0,1] neg_hi:[0,0,1]
	v_pk_fma_f32 v[6:7], v[2:3], v[6:7], v[42:43] op_sel:[0,0,1] op_sel_hi:[1,1,0]
	s_waitcnt vmcnt(40)
; DEV unsigned pk_bf16(float lo, float hi) { unsigned r; asm("v_cvt_pk_bf16_f32 %0, %1, %2" : "=v"(r) : "v"(lo), "v"(hi)); return r; }
; DEV float bflo(unsigned w) { return __uint_as_float(w << 16); }
; DEV float bfhi(unsigned w) { return __uint_as_float(w & 0xffff0000u); }
; DEV void ph_carry(const P& p, int l, bool need) {
;     ...
;     for (int blk = 0; blk < 17; ++blk) {
;       unsigned v[8]; int rows[8];
; #pragma unroll
;       for (int e = 0; e < 8; ++e) {
;         int r;
;         if (blk == 0) r = 1024 + b * 8 + (dir ? 7 - e : e);
;         else { const int j = (blk - 1) * 8 + e; r = b * 128 + (dir ? 127 - j : j); }
;         rows[e] = r; v[e] = S[(size_t)r * 4096];
;       }
; #pragma unroll
;       for (int e = 0; e < 8; ++e) {
;         S[(size_t)rows[e] * 4096] = pk_bf16(sr, si);
;         const float nr = at.x * sr - at.y * si + bflo(v[e]), ni = at.x * si + at.y * sr + bfhi(v[e]);
;         sr = nr; si = ni;
;       }
	v_lshlrev_b32_e32 v8, 16, v63
	v_and_b32_e32 v9, 0xffff0000, v63
	v_mov_b32_e32 v45, v7
	v_pk_add_f32 v[6:7], v[44:45], v[8:9]
	v_cvt_pk_bf16_f32 v46, v6, v7
	global_store_dword v[86:87], v46, off
	v_pk_mul_f32 v[42:43], v[4:5], v[6:7]
	v_lshl_add_u64 v[86:87], v[86:87], 0, v[88:89]
	v_pk_fma_f32 v[44:45], v[2:3], v[6:7], v[42:43] op_sel:[0,0,1] op_sel_hi:[1,1,0] neg_lo:[0,0,1] neg_hi:[0,0,1]
	v_pk_fma_f32 v[6:7], v[2:3], v[6:7], v[42:43] op_sel:[0,0,1] op_sel_hi:[1,1,0]
	s_waitcnt vmcnt(40)
	v_lshlrev_b32_e32 v8, 16, v64
	v_and_b32_e32 v9, 0xffff0000, v64
	v_mov_b32_e32 v45, v7
	v_pk_add_f32 v[6:7], v[44:45], v[8:9]
	v_cvt_pk_bf16_f32 v47, v6, v7
	global_store_dword v[86:87], v47, off
	v_pk_mul_f32 v[42:43], v[4:5], v[6:7]
	v_lshl_add_u64 v[86:87], v[86:87], 0, v[88:89]
	v_pk_fma_f32 v[44:45], v[2:3], v[6:7], v[42:43] op_sel:[0,0,1] op_sel_hi:[1,1,0] neg_lo:[0,0,1] neg_hi:[0,0,1]
	v_pk_fma_f32 v[6:7], v[2:3], v[6:7], v[42:43] op_sel:[0,0,1] op_sel_hi:[1,1,0]
	s_waitcnt vmcnt(40)
	v_lshlrev_b32_e32 v8, 16, v65
	v_and_b32_e32 v9, 0xffff0000, v65
	v_mov_b32_e32 v45, v7
	v_pk_add_f32 v[6:7], v[44:45], v[8:9]
	v_cvt_pk_bf16_f32 v46, v6, v7
	global_store_dword v[86:87], v46, off
	v_pk_mul_f32 v[42:43], v[4:5], v[6:7]
	v_lshl_add_u64 v[86:87], v[86:87], 0, v[88:89]
	v_pk_fma_f32 v[44:45], v[2:3], v[6:7], v[42:43] op_sel:[0,0,1] op_sel_hi:[1,1,0] neg_lo:[0,0,1] neg_hi:[0,0,1]
	v_pk_fma_f32 v[6:7], v[2:3], v[6:7], v[42:43] op_sel:[0,0,1] op_sel_hi:[1,1,0]
	s_waitcnt vmcnt(40)
	v_lshlrev_b32_e32 v8, 16, v66
	v_and_b32_e32 v9, 0xffff0000, v66
	v_mov_b32_e32 v45, v7
	v_pk_add_f32 v[6:7], v[44:45], v[8:9]
	v_cvt_pk_bf16_f32 v47, v6, v7
	global_store_dword v[86:87], v47, off
	v_pk_mul_f32 v[42:43], v[4:5], v[6:7]
	v_lshl_add_u64 v[86:87], v[86:87], 0, v[88:89]
	v_pk_fma_f32 v[44:45], v[2:3], v[6:7], v[42:43] op_sel:[0,0,1] op_sel_hi:[1,1,0] neg_lo:[0,0,1] neg_hi:[0,0,1]
	v_pk_fma_f32 v[6:7], v[2:3], v[6:7], v[42:43] op_sel:[0,0,1] op_sel_hi:[1,1,0]
	s_waitcnt vmcnt(40)
	v_lshlrev_b32_e32 v8, 16, v67
	v_and_b32_e32 v9, 0xffff0000, v67
	v_mov_b32_e32 v45, v7
	v_pk_add_f32 v[6:7], v[44:45], v[8:9]
	global_load_dword v60, v[84:85], off
	v_lshl_add_u64 v[84:85], v[84:85], 0, v[88:89]
	global_load_dword v61, v[84:85], off
	v_lshl_add_u64 v[84:85], v[84:85], 0, v[88:89]
	global_load_dword v62, v[84:85], off
	v_lshl_add_u64 v[84:85], v[84:85], 0, v[88:89]
	global_load_dword v63, v[84:85], off
	v_lshl_add_u64 v[84:85], v[84:85], 0, v[88:89]
	global_load_dword v64, v[84:85], off
	v_lshl_add_u64 v[84:85], v[84:85], 0, v[88:89]
	global_load_dword v65, v[84:85], off
	v_lshl_add_u64 v[84:85], v[84:85], 0, v[88:89]
	global_load_dword v66, v[84:85], off
	v_lshl_add_u64 v[84:85], v[84:85], 0, v[88:89]
	global_load_dword v67, v[84:85], off
	v_lshl_add_u64 v[84:85], v[84:85], 0, v[88:89]
	v_cvt_pk_bf16_f32 v46, v6, v7
	global_store_dword v[86:87], v46, off
	v_pk_mul_f32 v[42:43], v[4:5], v[6:7]
	v_lshl_add_u64 v[86:87], v[86:87], 0, v[88:89]
	v_pk_fma_f32 v[44:45], v[2:3], v[6:7], v[42:43] op_sel:[0,0,1] op_sel_hi:[1,1,0] neg_lo:[0,0,1] neg_hi:[0,0,1]
	v_pk_fma_f32 v[6:7], v[2:3], v[6:7], v[42:43] op_sel:[0,0,1] op_sel_hi:[1,1,0]
	s_waitcnt vmcnt(48)
	v_lshlrev_b32_e32 v8, 16, v68
	v_and_b32_e32 v9, 0xffff0000, v68
	v_mov_b32_e32 v45, v7
	v_pk_add_f32 v[6:7], v[44:45], v[8:9]
	v_cvt_pk_bf16_f32 v47, v6, v7
	global_store_dword v[86:87], v47, off
	v_pk_mul_f32 v[42:43], v[4:5], v[6:7]
	v_lshl_add_u64 v[86:87], v[86:87], 0, v[88:89]
	v_pk_fma_f32 v[44:45], v[2:3], v[6:7], v[42:43] op_sel:[0,0,1] op_sel_hi:[1,1,0] neg_lo:[0,0,1] neg_hi:[0,0,1]
	v_pk_fma_f32 v[6:7], v[2:3], v[6:7], v[42:43] op_sel:[0,0,1] op_sel_hi:[1,1,0]
	s_waitcnt vmcnt(48)
	v_lshlrev_b32_e32 v8, 16, v69
	v_and_b32_e32 v9, 0xffff0000, v69
	v_mov_b32_e32 v45, v7
	v_pk_add_f32 v[6:7], v[44:45], v[8:9]
	v_cvt_pk_bf16_f32 v46, v6, v7
	global_store_dword v[86:87], v46, off
	v_pk_mul_f32 v[42:43], v[4:5], v[6:7]
	v_lshl_add_u64 v[86:87], v[86:87], 0, v[88:89]
	v_pk_fma_f32 v[44:45], v[2:3], v[6:7], v[42:43] op_sel:[0,0,1] op_sel_hi:[1,1,0] neg_lo:[0,0,1] neg_hi:[0,0,1]
	v_pk_fma_f32 v[6:7], v[2:3], v[6:7], v[42:43] op_sel:[0,0,1] op_sel_hi:[1,1,0]
	s_waitcnt vmcnt(48)
	v_lshlrev_b32_e32 v8, 16, v70
	v_and_b32_e32 v9, 0xffff0000, v70
	v_mov_b32_e32 v45, v7
	v_pk_add_f32 v[6:7], v[44:45], v[8:9]
	v_cvt_pk_bf16_f32 v47, v6, v7
	global_store_dword v[86:87], v47, off
	v_pk_mul_f32 v[42:43], v[4:5], v[6:7]
	v_lshl_add_u64 v[86:87], v[86:87], 0, v[88:89]
	v_pk_fma_f32 v[44:45], v[2:3], v[6:7], v[42:43] op_sel:[0,0,1] op_sel_hi:[1,1,0] neg_lo:[0,0,1] neg_hi:[0,0,1]
	v_pk_fma_f32 v[6:7], v[2:3], v[6:7], v[42:43] op_sel:[0,0,1] op_sel_hi:[1,1,0]
	s_waitcnt vmcnt(48)
	v_lshlrev_b32_e32 v8, 16, v71
	v_and_b32_e32 v9, 0xffff0000, v71
	v_mov_b32_e32 v45, v7
	v_pk_add_f32 v[6:7], v[44:45], v[8:9]
	v_cvt_pk_bf16_f32 v46, v6, v7
	global_store_dword v[86:87], v46, off
	v_pk_mul_f32 v[42:43], v[4:5], v[6:7]
	v_lshl_add_u64 v[86:87], v[86:87], 0, v[88:89]
	v_pk_fma_f32 v[44:45], v[2:3], v[6:7], v[42:43] op_sel:[0,0,1] op_sel_hi:[1,1,0] neg_lo:[0,0,1] neg_hi:[0,0,1]
	v_pk_fma_f32 v[6:7], v[2:3], v[6:7], v[42:43] op_sel:[0,0,1] op_sel_hi:[1,1,0]
	s_waitcnt vmcnt(48)
	v_lshlrev_b32_e32 v8, 16, v72
	v_and_b32_e32 v9, 0xffff0000, v72
	v_mov_b32_e32 v45, v7
	v_pk_add_f32 v[6:7], v[44:45], v[8:9]
	v_cvt_pk_bf16_f32 v47, v6, v7
	global_store_dword v[86:87], v47, off
	v_pk_mul_f32 v[42:43], v[4:5], v[6:7]
	v_lshl_add_u64 v[86:87], v[86:87], 0, v[88:89]
	v_pk_fma_f32 v[44:45], v[2:3], v[6:7], v[42:43] op_sel:[0,0,1] op_sel_hi:[1,1,0] neg_lo:[0,0,1] neg_hi:[0,0,1]
	v_pk_fma_f32 v[6:7], v[2:3], v[6:7], v[42:43] op_sel:[0,0,1] op_sel_hi:[1,1,0]
	s_waitcnt vmcnt(48)
; DEV unsigned pk_bf16(float lo, float hi) { unsigned r; asm("v_cvt_pk_bf16_f32 %0, %1, %2" : "=v"(r) : "v"(lo), "v"(hi)); return r; }
; DEV float bflo(unsigned w) { return __uint_as_float(w << 16); }
; DEV float bfhi(unsigned w) { return __uint_as_float(w & 0xffff0000u); }
; DEV void ph_carry(const P& p, int l, bool need) {
;     ...
;     for (int blk = 0; blk < 17; ++blk) {
;       unsigned v[8]; int rows[8];
; #pragma unroll
;       for (int e = 0; e < 8; ++e) {
;         int r;
;         if (blk == 0) r = 1024 + b * 8 + (dir ? 7 - e : e);
;         else { const int j = (blk - 1) * 8 + e; r = b * 128 + (dir ? 127 - j : j); }
;         rows[e] = r; v[e] = S[(size_t)r * 4096];
;       }
; #pragma unroll
;       for (int e = 0; e < 8; ++e) {
;         S[(size_t)rows[e] * 4096] = pk_bf16(sr, si);
;         const float nr = at.x * sr - at.y * si + bflo(v[e]), ni = at.x * si + at.y * sr + bfhi(v[e]);
;         sr = nr; si = ni;
;       }
	v_lshlrev_b32_e32 v8, 16, v73
	v_and_b32_e32 v9, 0xffff0000, v73
	v_mov_b32_e32 v45, v7
	v_pk_add_f32 v[6:7], v[44:45], v[8:9]
	v_cvt_pk_bf16_f32 v46, v6, v7
	global_store_dword v[86:87], v46, off
	v_pk_mul_f32 v[42:43], v[4:5], v[6:7]
	v_lshl_add_u64 v[86:87], v[86:87], 0, v[88:89]
	v_pk_fma_f32 v[44:45], v[2:3], v[6:7], v[42:43] op_sel:[0,0,1] op_sel_hi:[1,1,0] neg_lo:[0,0,1] neg_hi:[0,0,1]
	v_pk_fma_f32 v[6:7], v[2:3], v[6:7], v[42:43] op_sel:[0,0,1] op_sel_hi:[1,1,0]
	s_waitcnt vmcnt(48)
	v_lshlrev_b32_e32 v8, 16, v74
	v_and_b32_e32 v9, 0xffff0000, v74
	v_mov_b32_e32 v45, v7
	v_pk_add_f32 v[6:7], v[44:45], v[8:9]
	v_cvt_pk_bf16_f32 v47, v6, v7
	global_store_dword v[86:87], v47, off
	v_pk_mul_f32 v[42:43], v[4:5], v[6:7]
	v_lshl_add_u64 v[86:87], v[86:87], 0, v[88:89]
	v_pk_fma_f32 v[44:45], v[2:3], v[6:7], v[42:43] op_sel:[0,0,1] op_sel_hi:[1,1,0] neg_lo:[0,0,1] neg_hi:[0,0,1]
	v_pk_fma_f32 v[6:7], v[2:3], v[6:7], v[42:43] op_sel:[0,0,1] op_sel_hi:[1,1,0]
	s_waitcnt vmcnt(48)
	v_lshlrev_b32_e32 v8, 16, v75
	v_and_b32_e32 v9, 0xffff0000, v75
	v_mov_b32_e32 v45, v7
	v_pk_add_f32 v[6:7], v[44:45], v[8:9]
	global_load_dword v68, v[84:85], off
	v_lshl_add_u64 v[84:85], v[84:85], 0, v[88:89]
	global_load_dword v69, v[84:85], off
	v_lshl_add_u64 v[84:85], v[84:85], 0, v[88:89]
	global_load_dword v70, v[84:85], off
	v_lshl_add_u64 v[84:85], v[84:85], 0, v[88:89]
	global_load_dword v71, v[84:85], off
	v_lshl_add_u64 v[84:85], v[84:85], 0, v[88:89]
	global_load_dword v72, v[84:85], off
	v_lshl_add_u64 v[84:85], v[84:85], 0, v[88:89]
	global_load_dword v73, v[84:85], off
	v_lshl_add_u64 v[84:85], v[84:85], 0, v[88:89]
	global_load_dword v74, v[84:85], off
	v_lshl_add_u64 v[84:85], v[84:85], 0, v[88:89]
	global_load_dword v75, v[84:85], off
	v_lshl_add_u64 v[84:85], v[84:85], 0, v[88:89]
	v_cvt_pk_bf16_f32 v46, v6, v7
	global_store_dword v[86:87], v46, off
	v_pk_mul_f32 v[42:43], v[4:5], v[6:7]
	v_lshl_add_u64 v[86:87], v[86:87], 0, v[88:89]
	v_pk_fma_f32 v[44:45], v[2:3], v[6:7], v[42:43] op_sel:[0,0,1] op_sel_hi:[1,1,0] neg_lo:[0,0,1] neg_hi:[0,0,1]
	v_pk_fma_f32 v[6:7], v[2:3], v[6:7], v[42:43] op_sel:[0,0,1] op_sel_hi:[1,1,0]
	s_waitcnt vmcnt(56)
	v_lshlrev_b32_e32 v8, 16, v76
	v_and_b32_e32 v9, 0xffff0000, v76
	v_mov_b32_e32 v45, v7
	v_pk_add_f32 v[6:7], v[44:45], v[8:9]
	v_cvt_pk_bf16_f32 v47, v6, v7
	global_store_dword v[86:87], v47, off
	v_pk_mul_f32 v[42:43], v[4:5], v[6:7]
	v_lshl_add_u64 v[86:87], v[86:87], 0, v[88:89]
	v_pk_fma_f32 v[44:45], v[2:3], v[6:7], v[42:43] op_sel:[0,0,1] op_sel_hi:[1,1,0] neg_lo:[0,0,1] neg_hi:[0,0,1]
	v_pk_fma_f32 v[6:7], v[2:3], v[6:7], v[42:43] op_sel:[0,0,1] op_sel_hi:[1,1,0]
	s_waitcnt vmcnt(56)
	v_lshlrev_b32_e32 v8, 16, v77
	v_and_b32_e32 v9, 0xffff0000, v77
	v_mov_b32_e32 v45, v7
	v_pk_add_f32 v[6:7], v[44:45], v[8:9]
	v_cvt_pk_bf16_f32 v46, v6, v7
	global_store_dword v[86:87], v46, off
	v_pk_mul_f32 v[42:43], v[4:5], v[6:7]
	v_lshl_add_u64 v[86:87], v[86:87], 0, v[88:89]
	v_pk_fma_f32 v[44:45], v[2:3], v[6:7], v[42:43] op_sel:[0,0,1] op_sel_hi:[1,1,0] neg_lo:[0,0,1] neg_hi:[0,0,1]
	v_pk_fma_f32 v[6:7], v[2:3], v[6:7], v[42:43] op_sel:[0,0,1] op_sel_hi:[1,1,0]
	s_waitcnt vmcnt(56)
	v_lshlrev_b32_e32 v8, 16, v78
	v_and_b32_e32 v9, 0xffff0000, v78
	v_mov_b32_e32 v45, v7
	v_pk_add_f32 v[6:7], v[44:45], v[8:9]
	v_cvt_pk_bf16_f32 v47, v6, v7
	global_store_dword v[86:87], v47, off
	v_pk_mul_f32 v[42:43], v[4:5], v[6:7]
	v_lshl_add_u64 v[86:87], v[86:87], 0, v[88:89]
	v_pk_fma_f32 v[44:45], v[2:3], v[6:7], v[42:43] op_sel:[0,0,1] op_sel_hi:[1,1,0] neg_lo:[0,0,1] neg_hi:[0,0,1]
	v_pk_fma_f32 v[6:7], v[2:3], v[6:7], v[42:43] op_sel:[0,0,1] op_sel_hi:[1,1,0]
	s_waitcnt vmcnt(56)
	v_lshlrev_b32_e32 v8, 16, v79
	v_and_b32_e32 v9, 0xffff0000, v79
	v_mov_b32_e32 v45, v7
	v_pk_add_f32 v[6:7], v[44:45], v[8:9]
	v_cvt_pk_bf16_f32 v46, v6, v7
	global_store_dword v[86:87], v46, off
	v_pk_mul_f32 v[42:43], v[4:5], v[6:7]
	v_lshl_add_u64 v[86:87], v[86:87], 0, v[88:89]
	v_pk_fma_f32 v[44:45], v[2:3], v[6:7], v[42:43] op_sel:[0,0,1] op_sel_hi:[1,1,0] neg_lo:[0,0,1] neg_hi:[0,0,1]
	v_pk_fma_f32 v[6:7], v[2:3], v[6:7], v[42:43] op_sel:[0,0,1] op_sel_hi:[1,1,0]
	s_waitcnt vmcnt(56)
	v_lshlrev_b32_e32 v8, 16, v80
	v_and_b32_e32 v9, 0xffff0000, v80
	v_mov_b32_e32 v45, v7
	v_pk_add_f32 v[6:7], v[44:45], v[8:9]
	v_cvt_pk_bf16_f32 v47, v6, v7
	global_store_dword v[86:87], v47, off
	v_pk_mul_f32 v[42:43], v[4:5], v[6:7]
	v_lshl_add_u64 v[86:87], v[86:87], 0, v[88:89]
	v_pk_fma_f32 v[44:45], v[2:3], v[6:7], v[42:43] op_sel:[0,0,1] op_sel_hi:[1,1,0] neg_lo:[0,0,1] neg_hi:[0,0,1]
	v_pk_fma_f32 v[6:7], v[2:3], v[6:7], v[42:43] op_sel:[0,0,1] op_sel_hi:[1,1,0]
	s_waitcnt vmcnt(56)
	v_lshlrev_b32_e32 v8, 16, v81
	v_and_b32_e32 v9, 0xffff0000, v81
	v_mov_b32_e32 v45, v7
	v_pk_add_f32 v[6:7], v[44:45], v[8:9]
	v_cvt_pk_bf16_f32 v46, v6, v7
	global_store_dword v[86:87], v46, off
	v_pk_mul_f32 v[42:43], v[4:5], v[6:7]
	v_lshl_add_u64 v[86:87], v[86:87], 0, v[88:89]
	v_pk_fma_f32 v[44:45], v[2:3], v[6:7], v[42:43] op_sel:[0,0,1] op_sel_hi:[1,1,0] neg_lo:[0,0,1] neg_hi:[0,0,1]
	v_pk_fma_f32 v[6:7], v[2:3], v[6:7], v[42:43] op_sel:[0,0,1] op_sel_hi:[1,1,0]
	s_waitcnt vmcnt(56)
	v_lshlrev_b32_e32 v8, 16, v82
	v_and_b32_e32 v9, 0xffff0000, v82
	v_mov_b32_e32 v45, v7
	v_pk_add_f32 v[6:7], v[44:45], v[8:9]
	v_cvt_pk_bf16_f32 v47, v6, v7
	global_store_dword v[86:87], v47, off
	v_pk_mul_f32 v[42:43], v[4:5], v[6:7]
	v_lshl_add_u64 v[86:87], v[86:87], 0, v[88:89]
	v_pk_fma_f32 v[44:45], v[2:3], v[6:7], v[42:43] op_sel:[0,0,1] op_sel_hi:[1,1,0] neg_lo:[0,0,1] neg_hi:[0,0,1]
	v_pk_fma_f32 v[6:7], v[2:3], v[6:7], v[42:43] op_sel:[0,0,1] op_sel_hi:[1,1,0]
	s_waitcnt vmcnt(56)
; DEV unsigned pk_bf16(float lo, float hi) { unsigned r; asm("v_cvt_pk_bf16_f32 %0, %1, %2" : "=v"(r) : "v"(lo), "v"(hi)); return r; }
; DEV float bflo(unsigned w) { return __uint_as_float(w << 16); }
; DEV float bfhi(unsigned w) { return __uint_as_float(w & 0xffff0000u); }
; DEV void ph_carry(const P& p, int l, bool need) {
;     ...
;     for (int blk = 0; blk < 17; ++blk) {
;       unsigned v[8]; int rows[8];
; #pragma unroll
;       for (int e = 0; e < 8; ++e) {
;         int r;
;         if (blk == 0) r = 1024 + b * 8 + (dir ? 7 - e : e);
;         else { const int j = (blk - 1) * 8 + e; r = b * 128 + (dir ? 127 - j : j); }
;         rows[e] = r; v[e] = S[(size_t)r * 4096];
;       }
; #pragma unroll
;       for (int e = 0; e < 8; ++e) {
;         S[(size_t)rows[e] * 4096] = pk_bf16(sr, si);
;         const float nr = at.x * sr - at.y * si + bflo(v[e]), ni = at.x * si + at.y * sr + bfhi(v[e]);
;         sr = nr; si = ni;
;       }
	v_lshlrev_b32_e32 v8, 16, v83
	v_and_b32_e32 v9, 0xffff0000, v83
	v_mov_b32_e32 v45, v7
	v_pk_add_f32 v[6:7], v[44:45], v[8:9]
	global_load_dword v76, v[84:85], off
	v_lshl_add_u64 v[84:85], v[84:85], 0, v[88:89]
	global_load_dword v77, v[84:85], off
	v_lshl_add_u64 v[84:85], v[84:85], 0, v[88:89]
	global_load_dword v78, v[84:85], off
	v_lshl_add_u64 v[84:85], v[84:85], 0, v[88:89]
	global_load_dword v79, v[84:85], off
	v_lshl_add_u64 v[84:85], v[84:85], 0, v[88:89]
	global_load_dword v80, v[84:85], off
	v_lshl_add_u64 v[84:85], v[84:85], 0, v[88:89]
	global_load_dword v81, v[84:85], off
	v_lshl_add_u64 v[84:85], v[84:85], 0, v[88:89]
	global_load_dword v82, v[84:85], off
	v_lshl_add_u64 v[84:85], v[84:85], 0, v[88:89]
	global_load_dword v83, v[84:85], off
	v_lshl_add_u64 v[84:85], v[84:85], 0, v[88:89]
	v_cvt_pk_bf16_f32 v46, v6, v7
	global_store_dword v[86:87], v46, off
	v_pk_mul_f32 v[42:43], v[4:5], v[6:7]
	v_lshl_add_u64 v[86:87], v[86:87], 0, v[88:89]
	v_pk_fma_f32 v[44:45], v[2:3], v[6:7], v[42:43] op_sel:[0,0,1] op_sel_hi:[1,1,0] neg_lo:[0,0,1] neg_hi:[0,0,1]
	v_pk_fma_f32 v[6:7], v[2:3], v[6:7], v[42:43] op_sel:[0,0,1] op_sel_hi:[1,1,0]
	s_waitcnt vmcnt(56)
	v_lshlrev_b32_e32 v8, 16, v52
	v_and_b32_e32 v9, 0xffff0000, v52
	v_mov_b32_e32 v45, v7
	v_pk_add_f32 v[6:7], v[44:45], v[8:9]
	v_cvt_pk_bf16_f32 v47, v6, v7
	global_store_dword v[86:87], v47, off
	v_pk_mul_f32 v[42:43], v[4:5], v[6:7]
	v_lshl_add_u64 v[86:87], v[86:87], 0, v[88:89]
	v_pk_fma_f32 v[44:45], v[2:3], v[6:7], v[42:43] op_sel:[0,0,1] op_sel_hi:[1,1,0] neg_lo:[0,0,1] neg_hi:[0,0,1]
	v_pk_fma_f32 v[6:7], v[2:3], v[6:7], v[42:43] op_sel:[0,0,1] op_sel_hi:[1,1,0]
	s_waitcnt vmcnt(56)
	v_lshlrev_b32_e32 v8, 16, v53
	v_and_b32_e32 v9, 0xffff0000, v53
	v_mov_b32_e32 v45, v7
	v_pk_add_f32 v[6:7], v[44:45], v[8:9]
	v_cvt_pk_bf16_f32 v46, v6, v7
	global_store_dword v[86:87], v46, off
	v_pk_mul_f32 v[42:43], v[4:5], v[6:7]
	v_lshl_add_u64 v[86:87], v[86:87], 0, v[88:89]
	v_pk_fma_f32 v[44:45], v[2:3], v[6:7], v[42:43] op_sel:[0,0,1] op_sel_hi:[1,1,0] neg_lo:[0,0,1] neg_hi:[0,0,1]
	v_pk_fma_f32 v[6:7], v[2:3], v[6:7], v[42:43] op_sel:[0,0,1] op_sel_hi:[1,1,0]
	s_waitcnt vmcnt(56)
	v_lshlrev_b32_e32 v8, 16, v54
	v_and_b32_e32 v9, 0xffff0000, v54
	v_mov_b32_e32 v45, v7
	v_pk_add_f32 v[6:7], v[44:45], v[8:9]
	v_cvt_pk_bf16_f32 v47, v6, v7
	global_store_dword v[86:87], v47, off
	v_pk_mul_f32 v[42:43], v[4:5], v[6:7]
	v_lshl_add_u64 v[86:87], v[86:87], 0, v[88:89]
	v_pk_fma_f32 v[44:45], v[2:3], v[6:7], v[42:43] op_sel:[0,0,1] op_sel_hi:[1,1,0] neg_lo:[0,0,1] neg_hi:[0,0,1]
	v_pk_fma_f32 v[6:7], v[2:3], v[6:7], v[42:43] op_sel:[0,0,1] op_sel_hi:[1,1,0]
	s_waitcnt vmcnt(56)
	v_lshlrev_b32_e32 v8, 16, v55
	v_and_b32_e32 v9, 0xffff0000, v55
	v_mov_b32_e32 v45, v7
	v_pk_add_f32 v[6:7], v[44:45], v[8:9]
	v_cvt_pk_bf16_f32 v46, v6, v7
	global_store_dword v[86:87], v46, off
	v_pk_mul_f32 v[42:43], v[4:5], v[6:7]
	v_lshl_add_u64 v[86:87], v[86:87], 0, v[88:89]
	v_pk_fma_f32 v[44:45], v[2:3], v[6:7], v[42:43] op_sel:[0,0,1] op_sel_hi:[1,1,0] neg_lo:[0,0,1] neg_hi:[0,0,1]
	v_pk_fma_f32 v[6:7], v[2:3], v[6:7], v[42:43] op_sel:[0,0,1] op_sel_hi:[1,1,0]
	s_waitcnt vmcnt(56)
	v_lshlrev_b32_e32 v8, 16, v56
	v_and_b32_e32 v9, 0xffff0000, v56
	v_mov_b32_e32 v45, v7
	v_pk_add_f32 v[6:7], v[44:45], v[8:9]
	v_cvt_pk_bf16_f32 v47, v6, v7
	global_store_dword v[86:87], v47, off
	v_pk_mul_f32 v[42:43], v[4:5], v[6:7]
	v_lshl_add_u64 v[86:87], v[86:87], 0, v[88:89]
	v_pk_fma_f32 v[44:45], v[2:3], v[6:7], v[42:43] op_sel:[0,0,1] op_sel_hi:[1,1,0] neg_lo:[0,0,1] neg_hi:[0,0,1]
	v_pk_fma_f32 v[6:7], v[2:3], v[6:7], v[42:43] op_sel:[0,0,1] op_sel_hi:[1,1,0]
	s_waitcnt vmcnt(56)
	v_lshlrev_b32_e32 v8, 16, v57
	v_and_b32_e32 v9, 0xffff0000, v57
	v_mov_b32_e32 v45, v7
	v_pk_add_f32 v[6:7], v[44:45], v[8:9]
	v_cvt_pk_bf16_f32 v46, v6, v7
	global_store_dword v[86:87], v46, off
	v_pk_mul_f32 v[42:43], v[4:5], v[6:7]
	v_lshl_add_u64 v[86:87], v[86:87], 0, v[88:89]
	v_pk_fma_f32 v[44:45], v[2:3], v[6:7], v[42:43] op_sel:[0,0,1] op_sel_hi:[1,1,0] neg_lo:[0,0,1] neg_hi:[0,0,1]
	v_pk_fma_f32 v[6:7], v[2:3], v[6:7], v[42:43] op_sel:[0,0,1] op_sel_hi:[1,1,0]
	s_waitcnt vmcnt(56)
	v_lshlrev_b32_e32 v8, 16, v58
	v_and_b32_e32 v9, 0xffff0000, v58
	v_mov_b32_e32 v45, v7
	v_pk_add_f32 v[6:7], v[44:45], v[8:9]
	v_cvt_pk_bf16_f32 v47, v6, v7
	global_store_dword v[86:87], v47, off
	v_pk_mul_f32 v[42:43], v[4:5], v[6:7]
	v_lshl_add_u64 v[86:87], v[86:87], 0, v[88:89]
	v_pk_fma_f32 v[44:45], v[2:3], v[6:7], v[42:43] op_sel:[0,0,1] op_sel_hi:[1,1,0] neg_lo:[0,0,1] neg_hi:[0,0,1]
	v_pk_fma_f32 v[6:7], v[2:3], v[6:7], v[42:43] op_sel:[0,0,1] op_sel_hi:[1,1,0]
	s_waitcnt vmcnt(56)
	v_lshlrev_b32_e32 v8, 16, v59
	v_and_b32_e32 v9, 0xffff0000, v59
	v_mov_b32_e32 v45, v7
	v_pk_add_f32 v[6:7], v[44:45], v[8:9]
	global_load_dword v52, v[84:85], off
	v_lshl_add_u64 v[84:85], v[84:85], 0, v[88:89]
	global_load_dword v53, v[84:85], off
	v_lshl_add_u64 v[84:85], v[84:85], 0, v[88:89]
	global_load_dword v54, v[84:85], off
	v_lshl_add_u64 v[84:85], v[84:85], 0, v[88:89]
	global_load_dword v55, v[84:85], off
	v_lshl_add_u64 v[84:85], v[84:85], 0, v[88:89]
	global_load_dword v56, v[84:85], off
	v_lshl_add_u64 v[84:85], v[84:85], 0, v[88:89]
	global_load_dword v57, v[84:85], off
	v_lshl_add_u64 v[84:85], v[84:85], 0, v[88:89]
	global_load_dword v58, v[84:85], off
	v_lshl_add_u64 v[84:85], v[84:85], 0, v[88:89]
	global_load_dword v59, v[84:85], off
	v_lshl_add_u64 v[84:85], v[84:85], 0, v[88:89]
	v_cvt_pk_bf16_f32 v46, v6, v7
	global_store_dword v[86:87], v46, off
	v_pk_mul_f32 v[42:43], v[4:5], v[6:7]
	v_lshl_add_u64 v[86:87], v[86:87], 0, v[88:89]
	v_pk_fma_f32 v[44:45], v[2:3], v[6:7], v[42:43] op_sel:[0,0,1] op_sel_hi:[1,1,0] neg_lo:[0,0,1] neg_hi:[0,0,1]
	v_pk_fma_f32 v[6:7], v[2:3], v[6:7], v[42:43] op_sel:[0,0,1] op_sel_hi:[1,1,0]
	s_waitcnt vmcnt(56)
; DEV unsigned pk_bf16(float lo, float hi) { unsigned r; asm("v_cvt_pk_bf16_f32 %0, %1, %2" : "=v"(r) : "v"(lo), "v"(hi)); return r; }
; DEV float bflo(unsigned w) { return __uint_as_float(w << 16); }
; DEV float bfhi(unsigned w) { return __uint_as_float(w & 0xffff0000u); }
; DEV void ph_carry(const P& p, int l, bool need) {
;     ...
;     for (int blk = 0; blk < 17; ++blk) {
;       unsigned v[8]; int rows[8];
; #pragma unroll
;       for (int e = 0; e < 8; ++e) {
;         int r;
;         if (blk == 0) r = 1024 + b * 8 + (dir ? 7 - e : e);
;         else { const int j = (blk - 1) * 8 + e; r = b * 128 + (dir ? 127 - j : j); }
;         rows[e] = r; v[e] = S[(size_t)r * 4096];
;       }
; #pragma unroll
;       for (int e = 0; e < 8; ++e) {
;         S[(size_t)rows[e] * 4096] = pk_bf16(sr, si);
;         const float nr = at.x * sr - at.y * si + bflo(v[e]), ni = at.x * si + at.y * sr + bfhi(v[e]);
;         sr = nr; si = ni;
;       }
	v_lshlrev_b32_e32 v8, 16, v60
	v_and_b32_e32 v9, 0xffff0000, v60
	v_mov_b32_e32 v45, v7
	v_pk_add_f32 v[6:7], v[44:45], v[8:9]
	v_cvt_pk_bf16_f32 v47, v6, v7
	global_store_dword v[86:87], v47, off
	v_pk_mul_f32 v[42:43], v[4:5], v[6:7]
	v_lshl_add_u64 v[86:87], v[86:87], 0, v[88:89]
	v_pk_fma_f32 v[44:45], v[2:3], v[6:7], v[42:43] op_sel:[0,0,1] op_sel_hi:[1,1,0] neg_lo:[0,0,1] neg_hi:[0,0,1]
	v_pk_fma_f32 v[6:7], v[2:3], v[6:7], v[42:43] op_sel:[0,0,1] op_sel_hi:[1,1,0]
	s_waitcnt vmcnt(56)
	v_lshlrev_b32_e32 v8, 16, v61
	v_and_b32_e32 v9, 0xffff0000, v61
	v_mov_b32_e32 v45, v7
	v_pk_add_f32 v[6:7], v[44:45], v[8:9]
	v_cvt_pk_bf16_f32 v46, v6, v7
	global_store_dword v[86:87], v46, off
	v_pk_mul_f32 v[42:43], v[4:5], v[6:7]
	v_lshl_add_u64 v[86:87], v[86:87], 0, v[88:89]
	v_pk_fma_f32 v[44:45], v[2:3], v[6:7], v[42:43] op_sel:[0,0,1] op_sel_hi:[1,1,0] neg_lo:[0,0,1] neg_hi:[0,0,1]
	v_pk_fma_f32 v[6:7], v[2:3], v[6:7], v[42:43] op_sel:[0,0,1] op_sel_hi:[1,1,0]
	s_waitcnt vmcnt(56)
	v_lshlrev_b32_e32 v8, 16, v62
	v_and_b32_e32 v9, 0xffff0000, v62
	v_mov_b32_e32 v45, v7
	v_pk_add_f32 v[6:7], v[44:45], v[8:9]
	v_cvt_pk_bf16_f32 v47, v6, v7
	global_store_dword v[86:87], v47, off
	v_pk_mul_f32 v[42:43], v[4:5], v[6:7]
	v_lshl_add_u64 v[86:87], v[86:87], 0, v[88:89]
	v_pk_fma_f32 v[44:45], v[2:3], v[6:7], v[42:43] op_sel:[0,0,1] op_sel_hi:[1,1,0] neg_lo:[0,0,1] neg_hi:[0,0,1]
	v_pk_fma_f32 v[6:7], v[2:3], v[6:7], v[42:43] op_sel:[0,0,1] op_sel_hi:[1,1,0]
	s_waitcnt vmcnt(56)
	v_lshlrev_b32_e32 v8, 16, v63
	v_and_b32_e32 v9, 0xffff0000, v63
	v_mov_b32_e32 v45, v7
	v_pk_add_f32 v[6:7], v[44:45], v[8:9]
	v_cvt_pk_bf16_f32 v46, v6, v7
	global_store_dword v[86:87], v46, off
	v_pk_mul_f32 v[42:43], v[4:5], v[6:7]
	v_lshl_add_u64 v[86:87], v[86:87], 0, v[88:89]
	v_pk_fma_f32 v[44:45], v[2:3], v[6:7], v[42:43] op_sel:[0,0,1] op_sel_hi:[1,1,0] neg_lo:[0,0,1] neg_hi:[0,0,1]
	v_pk_fma_f32 v[6:7], v[2:3], v[6:7], v[42:43] op_sel:[0,0,1] op_sel_hi:[1,1,0]
	s_waitcnt vmcnt(56)
	v_lshlrev_b32_e32 v8, 16, v64
	v_and_b32_e32 v9, 0xffff0000, v64
	v_mov_b32_e32 v45, v7
	v_pk_add_f32 v[6:7], v[44:45], v[8:9]
	v_cvt_pk_bf16_f32 v47, v6, v7
	global_store_dword v[86:87], v47, off
	v_pk_mul_f32 v[42:43], v[4:5], v[6:7]
	v_lshl_add_u64 v[86:87], v[86:87], 0, v[88:89]
	v_pk_fma_f32 v[44:45], v[2:3], v[6:7], v[42:43] op_sel:[0,0,1] op_sel_hi:[1,1,0] neg_lo:[0,0,1] neg_hi:[0,0,1]
	v_pk_fma_f32 v[6:7], v[2:3], v[6:7], v[42:43] op_sel:[0,0,1] op_sel_hi:[1,1,0]
	s_waitcnt vmcnt(56)
	v_lshlrev_b32_e32 v8, 16, v65
	v_and_b32_e32 v9, 0xffff0000, v65
	v_mov_b32_e32 v45, v7
	v_pk_add_f32 v[6:7], v[44:45], v[8:9]
	v_cvt_pk_bf16_f32 v46, v6, v7
	global_store_dword v[86:87], v46, off
	v_pk_mul_f32 v[42:43], v[4:5], v[6:7]
	v_lshl_add_u64 v[86:87], v[86:87], 0, v[88:89]
	v_pk_fma_f32 v[44:45], v[2:3], v[6:7], v[42:43] op_sel:[0,0,1] op_sel_hi:[1,1,0] neg_lo:[0,0,1] neg_hi:[0,0,1]
	v_pk_fma_f32 v[6:7], v[2:3], v[6:7], v[42:43] op_sel:[0,0,1] op_sel_hi:[1,1,0]
	s_waitcnt vmcnt(56)
	v_lshlrev_b32_e32 v8, 16, v66
	v_and_b32_e32 v9, 0xffff0000, v66
	v_mov_b32_e32 v45, v7
	v_pk_add_f32 v[6:7], v[44:45], v[8:9]
	v_cvt_pk_bf16_f32 v47, v6, v7
	global_store_dword v[86:87], v47, off
	v_pk_mul_f32 v[42:43], v[4:5], v[6:7]
	v_lshl_add_u64 v[86:87], v[86:87], 0, v[88:89]
	v_pk_fma_f32 v[44:45], v[2:3], v[6:7], v[42:43] op_sel:[0,0,1] op_sel_hi:[1,1,0] neg_lo:[0,0,1] neg_hi:[0,0,1]
	v_pk_fma_f32 v[6:7], v[2:3], v[6:7], v[42:43] op_sel:[0,0,1] op_sel_hi:[1,1,0]
	s_waitcnt vmcnt(56)
	v_lshlrev_b32_e32 v8, 16, v67
	v_and_b32_e32 v9, 0xffff0000, v67
	v_mov_b32_e32 v45, v7
	v_pk_add_f32 v[6:7], v[44:45], v[8:9]
	global_load_dword v60, v[84:85], off
	v_lshl_add_u64 v[84:85], v[84:85], 0, v[88:89]
	global_load_dword v61, v[84:85], off
	v_lshl_add_u64 v[84:85], v[84:85], 0, v[88:89]
	global_load_dword v62, v[84:85], off
	v_lshl_add_u64 v[84:85], v[84:85], 0, v[88:89]
	global_load_dword v63, v[84:85], off
	v_lshl_add_u64 v[84:85], v[84:85], 0, v[88:89]
	global_load_dword v64, v[84:85], off
	v_lshl_add_u64 v[84:85], v[84:85], 0, v[88:89]
	global_load_dword v65, v[84:85], off
	v_lshl_add_u64 v[84:85], v[84:85], 0, v[88:89]
	global_load_dword v66, v[84:85], off
	v_lshl_add_u64 v[84:85], v[84:85], 0, v[88:89]
	global_load_dword v67, v[84:85], off
	v_lshl_add_u64 v[84:85], v[84:85], 0, v[88:89]
	v_cvt_pk_bf16_f32 v46, v6, v7
	global_store_dword v[86:87], v46, off
	v_pk_mul_f32 v[42:43], v[4:5], v[6:7]
	v_lshl_add_u64 v[86:87], v[86:87], 0, v[88:89]
	v_pk_fma_f32 v[44:45], v[2:3], v[6:7], v[42:43] op_sel:[0,0,1] op_sel_hi:[1,1,0] neg_lo:[0,0,1] neg_hi:[0,0,1]
	v_pk_fma_f32 v[6:7], v[2:3], v[6:7], v[42:43] op_sel:[0,0,1] op_sel_hi:[1,1,0]
	s_waitcnt vmcnt(56)
	v_lshlrev_b32_e32 v8, 16, v68
	v_and_b32_e32 v9, 0xffff0000, v68
	v_mov_b32_e32 v45, v7
	v_pk_add_f32 v[6:7], v[44:45], v[8:9]
	v_cvt_pk_bf16_f32 v47, v6, v7
	global_store_dword v[86:87], v47, off
	v_pk_mul_f32 v[42:43], v[4:5], v[6:7]
	v_lshl_add_u64 v[86:87], v[86:87], 0, v[88:89]
	v_pk_fma_f32 v[44:45], v[2:3], v[6:7], v[42:43] op_sel:[0,0,1] op_sel_hi:[1,1,0] neg_lo:[0,0,1] neg_hi:[0,0,1]
	v_pk_fma_f32 v[6:7], v[2:3], v[6:7], v[42:43] op_sel:[0,0,1] op_sel_hi:[1,1,0]
	s_waitcnt vmcnt(56)
	v_lshlrev_b32_e32 v8, 16, v69
	v_and_b32_e32 v9, 0xffff0000, v69
	v_mov_b32_e32 v45, v7
	v_pk_add_f32 v[6:7], v[44:45], v[8:9]
	v_cvt_pk_bf16_f32 v46, v6, v7
	global_store_dword v[86:87], v46, off
	v_pk_mul_f32 v[42:43], v[4:5], v[6:7]
	v_lshl_add_u64 v[86:87], v[86:87], 0, v[88:89]
	v_pk_fma_f32 v[44:45], v[2:3], v[6:7], v[42:43] op_sel:[0,0,1] op_sel_hi:[1,1,0] neg_lo:[0,0,1] neg_hi:[0,0,1]
	v_pk_fma_f32 v[6:7], v[2:3], v[6:7], v[42:43] op_sel:[0,0,1] op_sel_hi:[1,1,0]
	s_waitcnt vmcnt(56)
; DEV unsigned pk_bf16(float lo, float hi) { unsigned r; asm("v_cvt_pk_bf16_f32 %0, %1, %2" : "=v"(r) : "v"(lo), "v"(hi)); return r; }
; DEV float bflo(unsigned w) { return __uint_as_float(w << 16); }
; DEV float bfhi(unsigned w) { return __uint_as_float(w & 0xffff0000u); }
; DEV void ph_carry(const P& p, int l, bool need) {
;     ...
;     for (int blk = 0; blk < 17; ++blk) {
;       unsigned v[8]; int rows[8];
; #pragma unroll
;       for (int e = 0; e < 8; ++e) {
;         int r;
;         if (blk == 0) r = 1024 + b * 8 + (dir ? 7 - e : e);
;         else { const int j = (blk - 1) * 8 + e; r = b * 128 + (dir ? 127 - j : j); }
;         rows[e] = r; v[e] = S[(size_t)r * 4096];
;       }
; #pragma unroll
;       for (int e = 0; e < 8; ++e) {
;         S[(size_t)rows[e] * 4096] = pk_bf16(sr, si);
;         const float nr = at.x * sr - at.y * si + bflo(v[e]), ni = at.x * si + at.y * sr + bfhi(v[e]);
;         sr = nr; si = ni;
;       }
	v_lshlrev_b32_e32 v8, 16, v70
	v_and_b32_e32 v9, 0xffff0000, v70
	v_mov_b32_e32 v45, v7
	v_pk_add_f32 v[6:7], v[44:45], v[8:9]
	v_cvt_pk_bf16_f32 v47, v6, v7
	global_store_dword v[86:87], v47, off
	v_pk_mul_f32 v[42:43], v[4:5], v[6:7]
	v_lshl_add_u64 v[86:87], v[86:87], 0, v[88:89]
	v_pk_fma_f32 v[44:45], v[2:3], v[6:7], v[42:43] op_sel:[0,0,1] op_sel_hi:[1,1,0] neg_lo:[0,0,1] neg_hi:[0,0,1]
	v_pk_fma_f32 v[6:7], v[2:3], v[6:7], v[42:43] op_sel:[0,0,1] op_sel_hi:[1,1,0]
	s_waitcnt vmcnt(56)
	v_lshlrev_b32_e32 v8, 16, v71
	v_and_b32_e32 v9, 0xffff0000, v71
	v_mov_b32_e32 v45, v7
	v_pk_add_f32 v[6:7], v[44:45], v[8:9]
	v_cvt_pk_bf16_f32 v46, v6, v7
	global_store_dword v[86:87], v46, off
	v_pk_mul_f32 v[42:43], v[4:5], v[6:7]
	v_lshl_add_u64 v[86:87], v[86:87], 0, v[88:89]
	v_pk_fma_f32 v[44:45], v[2:3], v[6:7], v[42:43] op_sel:[0,0,1] op_sel_hi:[1,1,0] neg_lo:[0,0,1] neg_hi:[0,0,1]
	v_pk_fma_f32 v[6:7], v[2:3], v[6:7], v[42:43] op_sel:[0,0,1] op_sel_hi:[1,1,0]
	s_waitcnt vmcnt(56)
	v_lshlrev_b32_e32 v8, 16, v72
	v_and_b32_e32 v9, 0xffff0000, v72
	v_mov_b32_e32 v45, v7
	v_pk_add_f32 v[6:7], v[44:45], v[8:9]
	v_cvt_pk_bf16_f32 v47, v6, v7
	global_store_dword v[86:87], v47, off
	v_pk_mul_f32 v[42:43], v[4:5], v[6:7]
	v_lshl_add_u64 v[86:87], v[86:87], 0, v[88:89]
	v_pk_fma_f32 v[44:45], v[2:3], v[6:7], v[42:43] op_sel:[0,0,1] op_sel_hi:[1,1,0] neg_lo:[0,0,1] neg_hi:[0,0,1]
	v_pk_fma_f32 v[6:7], v[2:3], v[6:7], v[42:43] op_sel:[0,0,1] op_sel_hi:[1,1,0]
	s_waitcnt vmcnt(56)
	v_lshlrev_b32_e32 v8, 16, v73
	v_and_b32_e32 v9, 0xffff0000, v73
	v_mov_b32_e32 v45, v7
	v_pk_add_f32 v[6:7], v[44:45], v[8:9]
	v_cvt_pk_bf16_f32 v46, v6, v7
	global_store_dword v[86:87], v46, off
	v_pk_mul_f32 v[42:43], v[4:5], v[6:7]
	v_lshl_add_u64 v[86:87], v[86:87], 0, v[88:89]
	v_pk_fma_f32 v[44:45], v[2:3], v[6:7], v[42:43] op_sel:[0,0,1] op_sel_hi:[1,1,0] neg_lo:[0,0,1] neg_hi:[0,0,1]
	v_pk_fma_f32 v[6:7], v[2:3], v[6:7], v[42:43] op_sel:[0,0,1] op_sel_hi:[1,1,0]
	s_waitcnt vmcnt(56)
	v_lshlrev_b32_e32 v8, 16, v74
	v_and_b32_e32 v9, 0xffff0000, v74
	v_mov_b32_e32 v45, v7
	v_pk_add_f32 v[6:7], v[44:45], v[8:9]
	v_cvt_pk_bf16_f32 v47, v6, v7
	global_store_dword v[86:87], v47, off
	v_pk_mul_f32 v[42:43], v[4:5], v[6:7]
	v_lshl_add_u64 v[86:87], v[86:87], 0, v[88:89]
	v_pk_fma_f32 v[44:45], v[2:3], v[6:7], v[42:43] op_sel:[0,0,1] op_sel_hi:[1,1,0] neg_lo:[0,0,1] neg_hi:[0,0,1]
	v_pk_fma_f32 v[6:7], v[2:3], v[6:7], v[42:43] op_sel:[0,0,1] op_sel_hi:[1,1,0]
	s_waitcnt vmcnt(56)
	v_lshlrev_b32_e32 v8, 16, v75
	v_and_b32_e32 v9, 0xffff0000, v75
	v_mov_b32_e32 v45, v7
	v_pk_add_f32 v[6:7], v[44:45], v[8:9]
	global_load_dword v68, v[84:85], off
	v_lshl_add_u64 v[84:85], v[84:85], 0, v[88:89]
	global_load_dword v69, v[84:85], off
	v_lshl_add_u64 v[84:85], v[84:85], 0, v[88:89]
	global_load_dword v70, v[84:85], off
	v_lshl_add_u64 v[84:85], v[84:85], 0, v[88:89]
	global_load_dword v71, v[84:85], off
	v_lshl_add_u64 v[84:85], v[84:85], 0, v[88:89]
	global_load_dword v72, v[84:85], off
	v_lshl_add_u64 v[84:85], v[84:85], 0, v[88:89]
	global_load_dword v73, v[84:85], off
	v_lshl_add_u64 v[84:85], v[84:85], 0, v[88:89]
	global_load_dword v74, v[84:85], off
	v_lshl_add_u64 v[84:85], v[84:85], 0, v[88:89]
	global_load_dword v75, v[84:85], off
	v_lshl_add_u64 v[84:85], v[84:85], 0, v[88:89]
	v_cvt_pk_bf16_f32 v46, v6, v7
	global_store_dword v[86:87], v46, off
	v_pk_mul_f32 v[42:43], v[4:5], v[6:7]
	v_lshl_add_u64 v[86:87], v[86:87], 0, v[88:89]
	v_pk_fma_f32 v[44:45], v[2:3], v[6:7], v[42:43] op_sel:[0,0,1] op_sel_hi:[1,1,0] neg_lo:[0,0,1] neg_hi:[0,0,1]
	v_pk_fma_f32 v[6:7], v[2:3], v[6:7], v[42:43] op_sel:[0,0,1] op_sel_hi:[1,1,0]
	s_waitcnt vmcnt(56)
	v_lshlrev_b32_e32 v8, 16, v76
	v_and_b32_e32 v9, 0xffff0000, v76
	v_mov_b32_e32 v45, v7
	v_pk_add_f32 v[6:7], v[44:45], v[8:9]
	v_cvt_pk_bf16_f32 v47, v6, v7
	global_store_dword v[86:87], v47, off
	v_pk_mul_f32 v[42:43], v[4:5], v[6:7]
	v_lshl_add_u64 v[86:87], v[86:87], 0, v[88:89]
	v_pk_fma_f32 v[44:45], v[2:3], v[6:7], v[42:43] op_sel:[0,0,1] op_sel_hi:[1,1,0] neg_lo:[0,0,1] neg_hi:[0,0,1]
	v_pk_fma_f32 v[6:7], v[2:3], v[6:7], v[42:43] op_sel:[0,0,1] op_sel_hi:[1,1,0]
	s_waitcnt vmcnt(56)
	v_lshlrev_b32_e32 v8, 16, v77
	v_and_b32_e32 v9, 0xffff0000, v77
	v_mov_b32_e32 v45, v7
	v_pk_add_f32 v[6:7], v[44:45], v[8:9]
	v_cvt_pk_bf16_f32 v46, v6, v7
	global_store_dword v[86:87], v46, off
	v_pk_mul_f32 v[42:43], v[4:5], v[6:7]
	v_lshl_add_u64 v[86:87], v[86:87], 0, v[88:89]
	v_pk_fma_f32 v[44:45], v[2:3], v[6:7], v[42:43] op_sel:[0,0,1] op_sel_hi:[1,1,0] neg_lo:[0,0,1] neg_hi:[0,0,1]
	v_pk_fma_f32 v[6:7], v[2:3], v[6:7], v[42:43] op_sel:[0,0,1] op_sel_hi:[1,1,0]
	s_waitcnt vmcnt(56)
	v_lshlrev_b32_e32 v8, 16, v78
	v_and_b32_e32 v9, 0xffff0000, v78
	v_mov_b32_e32 v45, v7
	v_pk_add_f32 v[6:7], v[44:45], v[8:9]
	v_cvt_pk_bf16_f32 v47, v6, v7
	global_store_dword v[86:87], v47, off
	v_pk_mul_f32 v[42:43], v[4:5], v[6:7]
	v_lshl_add_u64 v[86:87], v[86:87], 0, v[88:89]
	v_pk_fma_f32 v[44:45], v[2:3], v[6:7], v[42:43] op_sel:[0,0,1] op_sel_hi:[1,1,0] neg_lo:[0,0,1] neg_hi:[0,0,1]
	v_pk_fma_f32 v[6:7], v[2:3], v[6:7], v[42:43] op_sel:[0,0,1] op_sel_hi:[1,1,0]
	s_waitcnt vmcnt(56)
	v_lshlrev_b32_e32 v8, 16, v79
	v_and_b32_e32 v9, 0xffff0000, v79
	v_mov_b32_e32 v45, v7
	v_pk_add_f32 v[6:7], v[44:45], v[8:9]
	v_cvt_pk_bf16_f32 v46, v6, v7
	global_store_dword v[86:87], v46, off
	v_pk_mul_f32 v[42:43], v[4:5], v[6:7]
	v_lshl_add_u64 v[86:87], v[86:87], 0, v[88:89]
	v_pk_fma_f32 v[44:45], v[2:3], v[6:7], v[42:43] op_sel:[0,0,1] op_sel_hi:[1,1,0] neg_lo:[0,0,1] neg_hi:[0,0,1]
	v_pk_fma_f32 v[6:7], v[2:3], v[6:7], v[42:43] op_sel:[0,0,1] op_sel_hi:[1,1,0]
	s_waitcnt vmcnt(56)
; DEV unsigned pk_bf16(float lo, float hi) { unsigned r; asm("v_cvt_pk_bf16_f32 %0, %1, %2" : "=v"(r) : "v"(lo), "v"(hi)); return r; }
; DEV float bflo(unsigned w) { return __uint_as_float(w << 16); }
; DEV float bfhi(unsigned w) { return __uint_as_float(w & 0xffff0000u); }
; DEV void ph_carry(const P& p, int l, bool need) {
;     ...
;     for (int blk = 0; blk < 17; ++blk) {
;       unsigned v[8]; int rows[8];
; #pragma unroll
;       for (int e = 0; e < 8; ++e) {
;         int r;
;         if (blk == 0) r = 1024 + b * 8 + (dir ? 7 - e : e);
;         else { const int j = (blk - 1) * 8 + e; r = b * 128 + (dir ? 127 - j : j); }
;         rows[e] = r; v[e] = S[(size_t)r * 4096];
;       }
; #pragma unroll
;       for (int e = 0; e < 8; ++e) {
;         S[(size_t)rows[e] * 4096] = pk_bf16(sr, si);
;         const float nr = at.x * sr - at.y * si + bflo(v[e]), ni = at.x * si + at.y * sr + bfhi(v[e]);
;         sr = nr; si = ni;
;       }
	v_lshlrev_b32_e32 v8, 16, v80
	v_and_b32_e32 v9, 0xffff0000, v80
	v_mov_b32_e32 v45, v7
	v_pk_add_f32 v[6:7], v[44:45], v[8:9]
	v_cvt_pk_bf16_f32 v47, v6, v7
	global_store_dword v[86:87], v47, off
	v_pk_mul_f32 v[42:43], v[4:5], v[6:7]
	v_lshl_add_u64 v[86:87], v[86:87], 0, v[88:89]
	v_pk_fma_f32 v[44:45], v[2:3], v[6:7], v[42:43] op_sel:[0,0,1] op_sel_hi:[1,1,0] neg_lo:[0,0,1] neg_hi:[0,0,1]
	v_pk_fma_f32 v[6:7], v[2:3], v[6:7], v[42:43] op_sel:[0,0,1] op_sel_hi:[1,1,0]
	s_waitcnt vmcnt(56)
	v_lshlrev_b32_e32 v8, 16, v81
	v_and_b32_e32 v9, 0xffff0000, v81
	v_mov_b32_e32 v45, v7
	v_pk_add_f32 v[6:7], v[44:45], v[8:9]
	v_cvt_pk_bf16_f32 v46, v6, v7
	global_store_dword v[86:87], v46, off
	v_pk_mul_f32 v[42:43], v[4:5], v[6:7]
	v_lshl_add_u64 v[86:87], v[86:87], 0, v[88:89]
	v_pk_fma_f32 v[44:45], v[2:3], v[6:7], v[42:43] op_sel:[0,0,1] op_sel_hi:[1,1,0] neg_lo:[0,0,1] neg_hi:[0,0,1]
	v_pk_fma_f32 v[6:7], v[2:3], v[6:7], v[42:43] op_sel:[0,0,1] op_sel_hi:[1,1,0]
	s_waitcnt vmcnt(56)
	v_lshlrev_b32_e32 v8, 16, v82
	v_and_b32_e32 v9, 0xffff0000, v82
	v_mov_b32_e32 v45, v7
	v_pk_add_f32 v[6:7], v[44:45], v[8:9]
	v_cvt_pk_bf16_f32 v47, v6, v7
	global_store_dword v[86:87], v47, off
	v_pk_mul_f32 v[42:43], v[4:5], v[6:7]
	v_lshl_add_u64 v[86:87], v[86:87], 0, v[88:89]
	v_pk_fma_f32 v[44:45], v[2:3], v[6:7], v[42:43] op_sel:[0,0,1] op_sel_hi:[1,1,0] neg_lo:[0,0,1] neg_hi:[0,0,1]
	v_pk_fma_f32 v[6:7], v[2:3], v[6:7], v[42:43] op_sel:[0,0,1] op_sel_hi:[1,1,0]
	s_waitcnt vmcnt(56)
	v_lshlrev_b32_e32 v8, 16, v83
	v_and_b32_e32 v9, 0xffff0000, v83
	v_mov_b32_e32 v45, v7
	v_pk_add_f32 v[6:7], v[44:45], v[8:9]
	global_load_dword v76, v[84:85], off
	v_lshl_add_u64 v[84:85], v[84:85], 0, v[88:89]
	global_load_dword v77, v[84:85], off
	v_lshl_add_u64 v[84:85], v[84:85], 0, v[88:89]
	global_load_dword v78, v[84:85], off
	v_lshl_add_u64 v[84:85], v[84:85], 0, v[88:89]
	global_load_dword v79, v[84:85], off
	v_lshl_add_u64 v[84:85], v[84:85], 0, v[88:89]
	global_load_dword v80, v[84:85], off
	v_lshl_add_u64 v[84:85], v[84:85], 0, v[88:89]
	global_load_dword v81, v[84:85], off
	v_lshl_add_u64 v[84:85], v[84:85], 0, v[88:89]
	global_load_dword v82, v[84:85], off
	v_lshl_add_u64 v[84:85], v[84:85], 0, v[88:89]
	global_load_dword v83, v[84:85], off
	v_lshl_add_u64 v[84:85], v[84:85], 0, v[88:89]
	v_cvt_pk_bf16_f32 v46, v6, v7
	global_store_dword v[86:87], v46, off
	v_pk_mul_f32 v[42:43], v[4:5], v[6:7]
	v_lshl_add_u64 v[86:87], v[86:87], 0, v[88:89]
	v_pk_fma_f32 v[44:45], v[2:3], v[6:7], v[42:43] op_sel:[0,0,1] op_sel_hi:[1,1,0] neg_lo:[0,0,1] neg_hi:[0,0,1]
	v_pk_fma_f32 v[6:7], v[2:3], v[6:7], v[42:43] op_sel:[0,0,1] op_sel_hi:[1,1,0]
	s_waitcnt vmcnt(56)
	v_lshlrev_b32_e32 v8, 16, v52
	v_and_b32_e32 v9, 0xffff0000, v52
	v_mov_b32_e32 v45, v7
	v_pk_add_f32 v[6:7], v[44:45], v[8:9]
	v_cvt_pk_bf16_f32 v47, v6, v7
	global_store_dword v[86:87], v47, off
	v_pk_mul_f32 v[42:43], v[4:5], v[6:7]
	v_lshl_add_u64 v[86:87], v[86:87], 0, v[88:89]
	v_pk_fma_f32 v[44:45], v[2:3], v[6:7], v[42:43] op_sel:[0,0,1] op_sel_hi:[1,1,0] neg_lo:[0,0,1] neg_hi:[0,0,1]
	v_pk_fma_f32 v[6:7], v[2:3], v[6:7], v[42:43] op_sel:[0,0,1] op_sel_hi:[1,1,0]
	s_waitcnt vmcnt(56)
	v_lshlrev_b32_e32 v8, 16, v53
	v_and_b32_e32 v9, 0xffff0000, v53
	v_mov_b32_e32 v45, v7
	v_pk_add_f32 v[6:7], v[44:45], v[8:9]
	v_cvt_pk_bf16_f32 v46, v6, v7
	global_store_dword v[86:87], v46, off
	v_pk_mul_f32 v[42:43], v[4:5], v[6:7]
	v_lshl_add_u64 v[86:87], v[86:87], 0, v[88:89]
	v_pk_fma_f32 v[44:45], v[2:3], v[6:7], v[42:43] op_sel:[0,0,1] op_sel_hi:[1,1,0] neg_lo:[0,0,1] neg_hi:[0,0,1]
	v_pk_fma_f32 v[6:7], v[2:3], v[6:7], v[42:43] op_sel:[0,0,1] op_sel_hi:[1,1,0]
	s_waitcnt vmcnt(56)
	v_lshlrev_b32_e32 v8, 16, v54
	v_and_b32_e32 v9, 0xffff0000, v54
	v_mov_b32_e32 v45, v7
	v_pk_add_f32 v[6:7], v[44:45], v[8:9]
	v_cvt_pk_bf16_f32 v47, v6, v7
	global_store_dword v[86:87], v47, off
	v_pk_mul_f32 v[42:43], v[4:5], v[6:7]
	v_lshl_add_u64 v[86:87], v[86:87], 0, v[88:89]
	v_pk_fma_f32 v[44:45], v[2:3], v[6:7], v[42:43] op_sel:[0,0,1] op_sel_hi:[1,1,0] neg_lo:[0,0,1] neg_hi:[0,0,1]
	v_pk_fma_f32 v[6:7], v[2:3], v[6:7], v[42:43] op_sel:[0,0,1] op_sel_hi:[1,1,0]
	s_waitcnt vmcnt(56)
	v_lshlrev_b32_e32 v8, 16, v55
	v_and_b32_e32 v9, 0xffff0000, v55
	v_mov_b32_e32 v45, v7
	v_pk_add_f32 v[6:7], v[44:45], v[8:9]
	v_cvt_pk_bf16_f32 v46, v6, v7
	global_store_dword v[86:87], v46, off
	v_pk_mul_f32 v[42:43], v[4:5], v[6:7]
	v_lshl_add_u64 v[86:87], v[86:87], 0, v[88:89]
	v_pk_fma_f32 v[44:45], v[2:3], v[6:7], v[42:43] op_sel:[0,0,1] op_sel_hi:[1,1,0] neg_lo:[0,0,1] neg_hi:[0,0,1]
	v_pk_fma_f32 v[6:7], v[2:3], v[6:7], v[42:43] op_sel:[0,0,1] op_sel_hi:[1,1,0]
	s_waitcnt vmcnt(56)
	v_lshlrev_b32_e32 v8, 16, v56
	v_and_b32_e32 v9, 0xffff0000, v56
	v_mov_b32_e32 v45, v7
	v_pk_add_f32 v[6:7], v[44:45], v[8:9]
	v_cvt_pk_bf16_f32 v47, v6, v7
	global_store_dword v[86:87], v47, off
	v_pk_mul_f32 v[42:43], v[4:5], v[6:7]
	v_lshl_add_u64 v[86:87], v[86:87], 0, v[88:89]
	v_pk_fma_f32 v[44:45], v[2:3], v[6:7], v[42:43] op_sel:[0,0,1] op_sel_hi:[1,1,0] neg_lo:[0,0,1] neg_hi:[0,0,1]
	v_pk_fma_f32 v[6:7], v[2:3], v[6:7], v[42:43] op_sel:[0,0,1] op_sel_hi:[1,1,0]
	s_waitcnt vmcnt(56)
	v_lshlrev_b32_e32 v8, 16, v57
	v_and_b32_e32 v9, 0xffff0000, v57
	v_mov_b32_e32 v45, v7
	v_pk_add_f32 v[6:7], v[44:45], v[8:9]
	v_cvt_pk_bf16_f32 v46, v6, v7
	global_store_dword v[86:87], v46, off
	v_pk_mul_f32 v[42:43], v[4:5], v[6:7]
	v_lshl_add_u64 v[86:87], v[86:87], 0, v[88:89]
	v_pk_fma_f32 v[44:45], v[2:3], v[6:7], v[42:43] op_sel:[0,0,1] op_sel_hi:[1,1,0] neg_lo:[0,0,1] neg_hi:[0,0,1]
	v_pk_fma_f32 v[6:7], v[2:3], v[6:7], v[42:43] op_sel:[0,0,1] op_sel_hi:[1,1,0]
	s_waitcnt vmcnt(56)
; DEV unsigned pk_bf16(float lo, float hi) { unsigned r; asm("v_cvt_pk_bf16_f32 %0, %1, %2" : "=v"(r) : "v"(lo), "v"(hi)); return r; }
; DEV float bflo(unsigned w) { return __uint_as_float(w << 16); }
; DEV float bfhi(unsigned w) { return __uint_as_float(w & 0xffff0000u); }
; DEV void ph_carry(const P& p, int l, bool need) {
;     ...
;     for (int blk = 0; blk < 17; ++blk) {
;       unsigned v[8]; int rows[8];
; #pragma unroll
;       for (int e = 0; e < 8; ++e) {
;         int r;
;         if (blk == 0) r = 1024 + b * 8 + (dir ? 7 - e : e);
;         else { const int j = (blk - 1) * 8 + e; r = b * 128 + (dir ? 127 - j : j); }
;         rows[e] = r; v[e] = S[(size_t)r * 4096];
;       }
; #pragma unroll
;       for (int e = 0; e < 8; ++e) {
;         S[(size_t)rows[e] * 4096] = pk_bf16(sr, si);
;         const float nr = at.x * sr - at.y * si + bflo(v[e]), ni = at.x * si + at.y * sr + bfhi(v[e]);
;         sr = nr; si = ni;
;       }
	v_lshlrev_b32_e32 v8, 16, v58
	v_and_b32_e32 v9, 0xffff0000, v58
	v_mov_b32_e32 v45, v7
	v_pk_add_f32 v[6:7], v[44:45], v[8:9]
	v_cvt_pk_bf16_f32 v47, v6, v7
	global_store_dword v[86:87], v47, off
	v_pk_mul_f32 v[42:43], v[4:5], v[6:7]
	v_lshl_add_u64 v[86:87], v[86:87], 0, v[88:89]
	v_pk_fma_f32 v[44:45], v[2:3], v[6:7], v[42:43] op_sel:[0,0,1] op_sel_hi:[1,1,0] neg_lo:[0,0,1] neg_hi:[0,0,1]
	v_pk_fma_f32 v[6:7], v[2:3], v[6:7], v[42:43] op_sel:[0,0,1] op_sel_hi:[1,1,0]
	s_waitcnt vmcnt(56)
	v_lshlrev_b32_e32 v8, 16, v59
	v_and_b32_e32 v9, 0xffff0000, v59
	v_mov_b32_e32 v45, v7
	v_pk_add_f32 v[6:7], v[44:45], v[8:9]
	global_load_dword v52, v[84:85], off
	v_lshl_add_u64 v[84:85], v[84:85], 0, v[88:89]
	global_load_dword v53, v[84:85], off
	v_lshl_add_u64 v[84:85], v[84:85], 0, v[88:89]
	global_load_dword v54, v[84:85], off
	v_lshl_add_u64 v[84:85], v[84:85], 0, v[88:89]
	global_load_dword v55, v[84:85], off
	v_lshl_add_u64 v[84:85], v[84:85], 0, v[88:89]
	global_load_dword v56, v[84:85], off
	v_lshl_add_u64 v[84:85], v[84:85], 0, v[88:89]
	global_load_dword v57, v[84:85], off
	v_lshl_add_u64 v[84:85], v[84:85], 0, v[88:89]
	global_load_dword v58, v[84:85], off
	v_lshl_add_u64 v[84:85], v[84:85], 0, v[88:89]
	global_load_dword v59, v[84:85], off
	v_lshl_add_u64 v[84:85], v[84:85], 0, v[88:89]
	v_cvt_pk_bf16_f32 v46, v6, v7
	global_store_dword v[86:87], v46, off
	v_pk_mul_f32 v[42:43], v[4:5], v[6:7]
	v_lshl_add_u64 v[86:87], v[86:87], 0, v[88:89]
	v_pk_fma_f32 v[44:45], v[2:3], v[6:7], v[42:43] op_sel:[0,0,1] op_sel_hi:[1,1,0] neg_lo:[0,0,1] neg_hi:[0,0,1]
	v_pk_fma_f32 v[6:7], v[2:3], v[6:7], v[42:43] op_sel:[0,0,1] op_sel_hi:[1,1,0]
	s_waitcnt vmcnt(56)
	v_lshlrev_b32_e32 v8, 16, v60
	v_and_b32_e32 v9, 0xffff0000, v60
	v_mov_b32_e32 v45, v7
	v_pk_add_f32 v[6:7], v[44:45], v[8:9]
	v_cvt_pk_bf16_f32 v47, v6, v7
	global_store_dword v[86:87], v47, off
	v_pk_mul_f32 v[42:43], v[4:5], v[6:7]
	v_lshl_add_u64 v[86:87], v[86:87], 0, v[88:89]
	v_pk_fma_f32 v[44:45], v[2:3], v[6:7], v[42:43] op_sel:[0,0,1] op_sel_hi:[1,1,0] neg_lo:[0,0,1] neg_hi:[0,0,1]
	v_pk_fma_f32 v[6:7], v[2:3], v[6:7], v[42:43] op_sel:[0,0,1] op_sel_hi:[1,1,0]
	s_waitcnt vmcnt(56)
	v_lshlrev_b32_e32 v8, 16, v61
	v_and_b32_e32 v9, 0xffff0000, v61
	v_mov_b32_e32 v45, v7
	v_pk_add_f32 v[6:7], v[44:45], v[8:9]
	v_cvt_pk_bf16_f32 v46, v6, v7
	global_store_dword v[86:87], v46, off
	v_pk_mul_f32 v[42:43], v[4:5], v[6:7]
	v_lshl_add_u64 v[86:87], v[86:87], 0, v[88:89]
	v_pk_fma_f32 v[44:45], v[2:3], v[6:7], v[42:43] op_sel:[0,0,1] op_sel_hi:[1,1,0] neg_lo:[0,0,1] neg_hi:[0,0,1]
	v_pk_fma_f32 v[6:7], v[2:3], v[6:7], v[42:43] op_sel:[0,0,1] op_sel_hi:[1,1,0]
	s_waitcnt vmcnt(56)
	v_lshlrev_b32_e32 v8, 16, v62
	v_and_b32_e32 v9, 0xffff0000, v62
	v_mov_b32_e32 v45, v7
	v_pk_add_f32 v[6:7], v[44:45], v[8:9]
	v_cvt_pk_bf16_f32 v47, v6, v7
	global_store_dword v[86:87], v47, off
	v_pk_mul_f32 v[42:43], v[4:5], v[6:7]
	v_lshl_add_u64 v[86:87], v[86:87], 0, v[88:89]
	v_pk_fma_f32 v[44:45], v[2:3], v[6:7], v[42:43] op_sel:[0,0,1] op_sel_hi:[1,1,0] neg_lo:[0,0,1] neg_hi:[0,0,1]
	v_pk_fma_f32 v[6:7], v[2:3], v[6:7], v[42:43] op_sel:[0,0,1] op_sel_hi:[1,1,0]
	s_waitcnt vmcnt(56)
	v_lshlrev_b32_e32 v8, 16, v63
	v_and_b32_e32 v9, 0xffff0000, v63
	v_mov_b32_e32 v45, v7
	v_pk_add_f32 v[6:7], v[44:45], v[8:9]
	v_cvt_pk_bf16_f32 v46, v6, v7
	global_store_dword v[86:87], v46, off
	v_pk_mul_f32 v[42:43], v[4:5], v[6:7]
	v_lshl_add_u64 v[86:87], v[86:87], 0, v[88:89]
	v_pk_fma_f32 v[44:45], v[2:3], v[6:7], v[42:43] op_sel:[0,0,1] op_sel_hi:[1,1,0] neg_lo:[0,0,1] neg_hi:[0,0,1]
	v_pk_fma_f32 v[6:7], v[2:3], v[6:7], v[42:43] op_sel:[0,0,1] op_sel_hi:[1,1,0]
	s_waitcnt vmcnt(56)
	v_lshlrev_b32_e32 v8, 16, v64
	v_and_b32_e32 v9, 0xffff0000, v64
	v_mov_b32_e32 v45, v7
	v_pk_add_f32 v[6:7], v[44:45], v[8:9]
	v_cvt_pk_bf16_f32 v47, v6, v7
	global_store_dword v[86:87], v47, off
	v_pk_mul_f32 v[42:43], v[4:5], v[6:7]
	v_lshl_add_u64 v[86:87], v[86:87], 0, v[88:89]
	v_pk_fma_f32 v[44:45], v[2:3], v[6:7], v[42:43] op_sel:[0,0,1] op_sel_hi:[1,1,0] neg_lo:[0,0,1] neg_hi:[0,0,1]
	v_pk_fma_f32 v[6:7], v[2:3], v[6:7], v[42:43] op_sel:[0,0,1] op_sel_hi:[1,1,0]
	s_waitcnt vmcnt(56)
	v_lshlrev_b32_e32 v8, 16, v65
	v_and_b32_e32 v9, 0xffff0000, v65
	v_mov_b32_e32 v45, v7
	v_pk_add_f32 v[6:7], v[44:45], v[8:9]
	v_cvt_pk_bf16_f32 v46, v6, v7
	global_store_dword v[86:87], v46, off
	v_pk_mul_f32 v[42:43], v[4:5], v[6:7]
	v_lshl_add_u64 v[86:87], v[86:87], 0, v[88:89]
	v_pk_fma_f32 v[44:45], v[2:3], v[6:7], v[42:43] op_sel:[0,0,1] op_sel_hi:[1,1,0] neg_lo:[0,0,1] neg_hi:[0,0,1]
	v_pk_fma_f32 v[6:7], v[2:3], v[6:7], v[42:43] op_sel:[0,0,1] op_sel_hi:[1,1,0]
	s_waitcnt vmcnt(56)
	v_lshlrev_b32_e32 v8, 16, v66
	v_and_b32_e32 v9, 0xffff0000, v66
	v_mov_b32_e32 v45, v7
	v_pk_add_f32 v[6:7], v[44:45], v[8:9]
	v_cvt_pk_bf16_f32 v47, v6, v7
	global_store_dword v[86:87], v47, off
	v_pk_mul_f32 v[42:43], v[4:5], v[6:7]
	v_lshl_add_u64 v[86:87], v[86:87], 0, v[88:89]
	v_pk_fma_f32 v[44:45], v[2:3], v[6:7], v[42:43] op_sel:[0,0,1] op_sel_hi:[1,1,0] neg_lo:[0,0,1] neg_hi:[0,0,1]
	v_pk_fma_f32 v[6:7], v[2:3], v[6:7], v[42:43] op_sel:[0,0,1] op_sel_hi:[1,1,0]
	s_waitcnt vmcnt(56)
; DEV unsigned pk_bf16(float lo, float hi) { unsigned r; asm("v_cvt_pk_bf16_f32 %0, %1, %2" : "=v"(r) : "v"(lo), "v"(hi)); return r; }
; DEV float bflo(unsigned w) { return __uint_as_float(w << 16); }
; DEV float bfhi(unsigned w) { return __uint_as_float(w & 0xffff0000u); }
; DEV void ph_carry(const P& p, int l, bool need) {
;     ...
;     for (int blk = 0; blk < 17; ++blk) {
;       unsigned v[8]; int rows[8];
; #pragma unroll
;       for (int e = 0; e < 8; ++e) {
;         int r;
;         if (blk == 0) r = 1024 + b * 8 + (dir ? 7 - e : e);
;         else { const int j = (blk - 1) * 8 + e; r = b * 128 + (dir ? 127 - j : j); }
;         rows[e] = r; v[e] = S[(size_t)r * 4096];
;       }
; #pragma unroll
;       for (int e = 0; e < 8; ++e) {
;         S[(size_t)rows[e] * 4096] = pk_bf16(sr, si);
;         const float nr = at.x * sr - at.y * si + bflo(v[e]), ni = at.x * si + at.y * sr + bfhi(v[e]);
;         sr = nr; si = ni;
;       }
	v_lshlrev_b32_e32 v8, 16, v67
	v_and_b32_e32 v9, 0xffff0000, v67
	v_mov_b32_e32 v45, v7
	v_pk_add_f32 v[6:7], v[44:45], v[8:9]
	global_load_dword v60, v[84:85], off
	v_lshl_add_u64 v[84:85], v[84:85], 0, v[88:89]
	global_load_dword v61, v[84:85], off
	v_lshl_add_u64 v[84:85], v[84:85], 0, v[88:89]
	global_load_dword v62, v[84:85], off
	v_lshl_add_u64 v[84:85], v[84:85], 0, v[88:89]
	global_load_dword v63, v[84:85], off
	v_lshl_add_u64 v[84:85], v[84:85], 0, v[88:89]
	global_load_dword v64, v[84:85], off
	v_lshl_add_u64 v[84:85], v[84:85], 0, v[88:89]
	global_load_dword v65, v[84:85], off
	v_lshl_add_u64 v[84:85], v[84:85], 0, v[88:89]
	global_load_dword v66, v[84:85], off
	v_lshl_add_u64 v[84:85], v[84:85], 0, v[88:89]
	global_load_dword v67, v[84:85], off
	v_lshl_add_u64 v[84:85], v[84:85], 0, v[88:89]
	v_cvt_pk_bf16_f32 v46, v6, v7
	global_store_dword v[86:87], v46, off
	v_pk_mul_f32 v[42:43], v[4:5], v[6:7]
	v_lshl_add_u64 v[86:87], v[86:87], 0, v[88:89]
	v_pk_fma_f32 v[44:45], v[2:3], v[6:7], v[42:43] op_sel:[0,0,1] op_sel_hi:[1,1,0] neg_lo:[0,0,1] neg_hi:[0,0,1]
	v_pk_fma_f32 v[6:7], v[2:3], v[6:7], v[42:43] op_sel:[0,0,1] op_sel_hi:[1,1,0]
	s_waitcnt vmcnt(56)
	v_lshlrev_b32_e32 v8, 16, v68
	v_and_b32_e32 v9, 0xffff0000, v68
	v_mov_b32_e32 v45, v7
	v_pk_add_f32 v[6:7], v[44:45], v[8:9]
	v_cvt_pk_bf16_f32 v47, v6, v7
	global_store_dword v[86:87], v47, off
	v_pk_mul_f32 v[42:43], v[4:5], v[6:7]
	v_lshl_add_u64 v[86:87], v[86:87], 0, v[88:89]
	v_pk_fma_f32 v[44:45], v[2:3], v[6:7], v[42:43] op_sel:[0,0,1] op_sel_hi:[1,1,0] neg_lo:[0,0,1] neg_hi:[0,0,1]
	v_pk_fma_f32 v[6:7], v[2:3], v[6:7], v[42:43] op_sel:[0,0,1] op_sel_hi:[1,1,0]
	s_waitcnt vmcnt(56)
	v_lshlrev_b32_e32 v8, 16, v69
	v_and_b32_e32 v9, 0xffff0000, v69
	v_mov_b32_e32 v45, v7
	v_pk_add_f32 v[6:7], v[44:45], v[8:9]
	v_cvt_pk_bf16_f32 v46, v6, v7
	global_store_dword v[86:87], v46, off
	v_pk_mul_f32 v[42:43], v[4:5], v[6:7]
	v_lshl_add_u64 v[86:87], v[86:87], 0, v[88:89]
	v_pk_fma_f32 v[44:45], v[2:3], v[6:7], v[42:43] op_sel:[0,0,1] op_sel_hi:[1,1,0] neg_lo:[0,0,1] neg_hi:[0,0,1]
	v_pk_fma_f32 v[6:7], v[2:3], v[6:7], v[42:43] op_sel:[0,0,1] op_sel_hi:[1,1,0]
	s_waitcnt vmcnt(56)
	v_lshlrev_b32_e32 v8, 16, v70
	v_and_b32_e32 v9, 0xffff0000, v70
	v_mov_b32_e32 v45, v7
	v_pk_add_f32 v[6:7], v[44:45], v[8:9]
	v_cvt_pk_bf16_f32 v47, v6, v7
	global_store_dword v[86:87], v47, off
	v_pk_mul_f32 v[42:43], v[4:5], v[6:7]
	v_lshl_add_u64 v[86:87], v[86:87], 0, v[88:89]
	v_pk_fma_f32 v[44:45], v[2:3], v[6:7], v[42:43] op_sel:[0,0,1] op_sel_hi:[1,1,0] neg_lo:[0,0,1] neg_hi:[0,0,1]
	v_pk_fma_f32 v[6:7], v[2:3], v[6:7], v[42:43] op_sel:[0,0,1] op_sel_hi:[1,1,0]
	s_waitcnt vmcnt(56)
	v_lshlrev_b32_e32 v8, 16, v71
	v_and_b32_e32 v9, 0xffff0000, v71
	v_mov_b32_e32 v45, v7
	v_pk_add_f32 v[6:7], v[44:45], v[8:9]
	v_cvt_pk_bf16_f32 v46, v6, v7
	global_store_dword v[86:87], v46, off
	v_pk_mul_f32 v[42:43], v[4:5], v[6:7]
	v_lshl_add_u64 v[86:87], v[86:87], 0, v[88:89]
	v_pk_fma_f32 v[44:45], v[2:3], v[6:7], v[42:43] op_sel:[0,0,1] op_sel_hi:[1,1,0] neg_lo:[0,0,1] neg_hi:[0,0,1]
	v_pk_fma_f32 v[6:7], v[2:3], v[6:7], v[42:43] op_sel:[0,0,1] op_sel_hi:[1,1,0]
	s_waitcnt vmcnt(56)
	v_lshlrev_b32_e32 v8, 16, v72
	v_and_b32_e32 v9, 0xffff0000, v72
	v_mov_b32_e32 v45, v7
	v_pk_add_f32 v[6:7], v[44:45], v[8:9]
	v_cvt_pk_bf16_f32 v47, v6, v7
	global_store_dword v[86:87], v47, off
	v_pk_mul_f32 v[42:43], v[4:5], v[6:7]
	v_lshl_add_u64 v[86:87], v[86:87], 0, v[88:89]
	v_pk_fma_f32 v[44:45], v[2:3], v[6:7], v[42:43] op_sel:[0,0,1] op_sel_hi:[1,1,0] neg_lo:[0,0,1] neg_hi:[0,0,1]
	v_pk_fma_f32 v[6:7], v[2:3], v[6:7], v[42:43] op_sel:[0,0,1] op_sel_hi:[1,1,0]
	s_waitcnt vmcnt(56)
	v_lshlrev_b32_e32 v8, 16, v73
	v_and_b32_e32 v9, 0xffff0000, v73
	v_mov_b32_e32 v45, v7
	v_pk_add_f32 v[6:7], v[44:45], v[8:9]
	v_cvt_pk_bf16_f32 v46, v6, v7
	global_store_dword v[86:87], v46, off
	v_pk_mul_f32 v[42:43], v[4:5], v[6:7]
	v_lshl_add_u64 v[86:87], v[86:87], 0, v[88:89]
	v_pk_fma_f32 v[44:45], v[2:3], v[6:7], v[42:43] op_sel:[0,0,1] op_sel_hi:[1,1,0] neg_lo:[0,0,1] neg_hi:[0,0,1]
	v_pk_fma_f32 v[6:7], v[2:3], v[6:7], v[42:43] op_sel:[0,0,1] op_sel_hi:[1,1,0]
	s_waitcnt vmcnt(56)
	v_lshlrev_b32_e32 v8, 16, v74
	v_and_b32_e32 v9, 0xffff0000, v74
	v_mov_b32_e32 v45, v7
	v_pk_add_f32 v[6:7], v[44:45], v[8:9]
	v_cvt_pk_bf16_f32 v47, v6, v7
	global_store_dword v[86:87], v47, off
	v_pk_mul_f32 v[42:43], v[4:5], v[6:7]
	v_lshl_add_u64 v[86:87], v[86:87], 0, v[88:89]
	v_pk_fma_f32 v[44:45], v[2:3], v[6:7], v[42:43] op_sel:[0,0,1] op_sel_hi:[1,1,0] neg_lo:[0,0,1] neg_hi:[0,0,1]
	v_pk_fma_f32 v[6:7], v[2:3], v[6:7], v[42:43] op_sel:[0,0,1] op_sel_hi:[1,1,0]
	s_waitcnt vmcnt(56)
	v_lshlrev_b32_e32 v8, 16, v75
	v_and_b32_e32 v9, 0xffff0000, v75
	v_mov_b32_e32 v45, v7
	v_pk_add_f32 v[6:7], v[44:45], v[8:9]
	global_load_dword v68, v[84:85], off
	v_lshl_add_u64 v[84:85], v[84:85], 0, v[88:89]
	global_load_dword v69, v[84:85], off
	v_lshl_add_u64 v[84:85], v[84:85], 0, v[88:89]
	global_load_dword v70, v[84:85], off
	v_lshl_add_u64 v[84:85], v[84:85], 0, v[88:89]
	global_load_dword v71, v[84:85], off
	v_lshl_add_u64 v[84:85], v[84:85], 0, v[88:89]
	global_load_dword v72, v[84:85], off
	v_lshl_add_u64 v[84:85], v[84:85], 0, v[88:89]
	global_load_dword v73, v[84:85], off
	v_lshl_add_u64 v[84:85], v[84:85], 0, v[88:89]
	global_load_dword v74, v[84:85], off
	v_lshl_add_u64 v[84:85], v[84:85], 0, v[88:89]
	global_load_dword v75, v[84:85], off
	v_lshl_add_u64 v[84:85], v[84:85], 0, v[88:89]
	v_cvt_pk_bf16_f32 v46, v6, v7
	global_store_dword v[86:87], v46, off
	v_pk_mul_f32 v[42:43], v[4:5], v[6:7]
	v_lshl_add_u64 v[86:87], v[86:87], 0, v[88:89]
	v_pk_fma_f32 v[44:45], v[2:3], v[6:7], v[42:43] op_sel:[0,0,1] op_sel_hi:[1,1,0] neg_lo:[0,0,1] neg_hi:[0,0,1]
	v_pk_fma_f32 v[6:7], v[2:3], v[6:7], v[42:43] op_sel:[0,0,1] op_sel_hi:[1,1,0]
	s_waitcnt vmcnt(56)
; DEV unsigned pk_bf16(float lo, float hi) { unsigned r; asm("v_cvt_pk_bf16_f32 %0, %1, %2" : "=v"(r) : "v"(lo), "v"(hi)); return r; }
; DEV float bflo(unsigned w) { return __uint_as_float(w << 16); }
; DEV float bfhi(unsigned w) { return __uint_as_float(w & 0xffff0000u); }
; DEV void ph_carry(const P& p, int l, bool need) {
;     ...
;     for (int blk = 0; blk < 17; ++blk) {
;       unsigned v[8]; int rows[8];
; #pragma unroll
;       for (int e = 0; e < 8; ++e) {
;         int r;
;         if (blk == 0) r = 1024 + b * 8 + (dir ? 7 - e : e);
;         else { const int j = (blk - 1) * 8 + e; r = b * 128 + (dir ? 127 - j : j); }
;         rows[e] = r; v[e] = S[(size_t)r * 4096];
;       }
; #pragma unroll
;       for (int e = 0; e < 8; ++e) {
;         S[(size_t)rows[e] * 4096] = pk_bf16(sr, si);
;         const float nr = at.x * sr - at.y * si + bflo(v[e]), ni = at.x * si + at.y * sr + bfhi(v[e]);
;         sr = nr; si = ni;
;       }
	v_lshlrev_b32_e32 v8, 16, v76
	v_and_b32_e32 v9, 0xffff0000, v76
	v_mov_b32_e32 v45, v7
	v_pk_add_f32 v[6:7], v[44:45], v[8:9]
	v_cvt_pk_bf16_f32 v47, v6, v7
	global_store_dword v[86:87], v47, off
	v_pk_mul_f32 v[42:43], v[4:5], v[6:7]
	v_lshl_add_u64 v[86:87], v[86:87], 0, v[88:89]
	v_pk_fma_f32 v[44:45], v[2:3], v[6:7], v[42:43] op_sel:[0,0,1] op_sel_hi:[1,1,0] neg_lo:[0,0,1] neg_hi:[0,0,1]
	v_pk_fma_f32 v[6:7], v[2:3], v[6:7], v[42:43] op_sel:[0,0,1] op_sel_hi:[1,1,0]
	s_waitcnt vmcnt(56)
	v_lshlrev_b32_e32 v8, 16, v77
	v_and_b32_e32 v9, 0xffff0000, v77
	v_mov_b32_e32 v45, v7
	v_pk_add_f32 v[6:7], v[44:45], v[8:9]
	v_cvt_pk_bf16_f32 v46, v6, v7
	global_store_dword v[86:87], v46, off
	v_pk_mul_f32 v[42:43], v[4:5], v[6:7]
	v_lshl_add_u64 v[86:87], v[86:87], 0, v[88:89]
	v_pk_fma_f32 v[44:45], v[2:3], v[6:7], v[42:43] op_sel:[0,0,1] op_sel_hi:[1,1,0] neg_lo:[0,0,1] neg_hi:[0,0,1]
	v_pk_fma_f32 v[6:7], v[2:3], v[6:7], v[42:43] op_sel:[0,0,1] op_sel_hi:[1,1,0]
	s_waitcnt vmcnt(56)
	v_lshlrev_b32_e32 v8, 16, v78
	v_and_b32_e32 v9, 0xffff0000, v78
	v_mov_b32_e32 v45, v7
	v_pk_add_f32 v[6:7], v[44:45], v[8:9]
	v_cvt_pk_bf16_f32 v47, v6, v7
	global_store_dword v[86:87], v47, off
	v_pk_mul_f32 v[42:43], v[4:5], v[6:7]
	v_lshl_add_u64 v[86:87], v[86:87], 0, v[88:89]
	v_pk_fma_f32 v[44:45], v[2:3], v[6:7], v[42:43] op_sel:[0,0,1] op_sel_hi:[1,1,0] neg_lo:[0,0,1] neg_hi:[0,0,1]
	v_pk_fma_f32 v[6:7], v[2:3], v[6:7], v[42:43] op_sel:[0,0,1] op_sel_hi:[1,1,0]
	s_waitcnt vmcnt(56)
	v_lshlrev_b32_e32 v8, 16, v79
	v_and_b32_e32 v9, 0xffff0000, v79
	v_mov_b32_e32 v45, v7
	v_pk_add_f32 v[6:7], v[44:45], v[8:9]
	v_cvt_pk_bf16_f32 v46, v6, v7
	global_store_dword v[86:87], v46, off
	v_pk_mul_f32 v[42:43], v[4:5], v[6:7]
	v_lshl_add_u64 v[86:87], v[86:87], 0, v[88:89]
	v_pk_fma_f32 v[44:45], v[2:3], v[6:7], v[42:43] op_sel:[0,0,1] op_sel_hi:[1,1,0] neg_lo:[0,0,1] neg_hi:[0,0,1]
	v_pk_fma_f32 v[6:7], v[2:3], v[6:7], v[42:43] op_sel:[0,0,1] op_sel_hi:[1,1,0]
	s_waitcnt vmcnt(56)
	v_lshlrev_b32_e32 v8, 16, v80
	v_and_b32_e32 v9, 0xffff0000, v80
	v_mov_b32_e32 v45, v7
	v_pk_add_f32 v[6:7], v[44:45], v[8:9]
	v_cvt_pk_bf16_f32 v47, v6, v7
	global_store_dword v[86:87], v47, off
	v_pk_mul_f32 v[42:43], v[4:5], v[6:7]
	v_lshl_add_u64 v[86:87], v[86:87], 0, v[88:89]
	v_pk_fma_f32 v[44:45], v[2:3], v[6:7], v[42:43] op_sel:[0,0,1] op_sel_hi:[1,1,0] neg_lo:[0,0,1] neg_hi:[0,0,1]
	v_pk_fma_f32 v[6:7], v[2:3], v[6:7], v[42:43] op_sel:[0,0,1] op_sel_hi:[1,1,0]
	s_waitcnt vmcnt(56)
	v_lshlrev_b32_e32 v8, 16, v81
	v_and_b32_e32 v9, 0xffff0000, v81
	v_mov_b32_e32 v45, v7
	v_pk_add_f32 v[6:7], v[44:45], v[8:9]
	v_cvt_pk_bf16_f32 v46, v6, v7
	global_store_dword v[86:87], v46, off
	v_pk_mul_f32 v[42:43], v[4:5], v[6:7]
	v_lshl_add_u64 v[86:87], v[86:87], 0, v[88:89]
	v_pk_fma_f32 v[44:45], v[2:3], v[6:7], v[42:43] op_sel:[0,0,1] op_sel_hi:[1,1,0] neg_lo:[0,0,1] neg_hi:[0,0,1]
	v_pk_fma_f32 v[6:7], v[2:3], v[6:7], v[42:43] op_sel:[0,0,1] op_sel_hi:[1,1,0]
	s_waitcnt vmcnt(56)
	v_lshlrev_b32_e32 v8, 16, v82
	v_and_b32_e32 v9, 0xffff0000, v82
	v_mov_b32_e32 v45, v7
	v_pk_add_f32 v[6:7], v[44:45], v[8:9]
	v_cvt_pk_bf16_f32 v47, v6, v7
	global_store_dword v[86:87], v47, off
	v_pk_mul_f32 v[42:43], v[4:5], v[6:7]
	v_lshl_add_u64 v[86:87], v[86:87], 0, v[88:89]
	v_pk_fma_f32 v[44:45], v[2:3], v[6:7], v[42:43] op_sel:[0,0,1] op_sel_hi:[1,1,0] neg_lo:[0,0,1] neg_hi:[0,0,1]
	v_pk_fma_f32 v[6:7], v[2:3], v[6:7], v[42:43] op_sel:[0,0,1] op_sel_hi:[1,1,0]
	s_waitcnt vmcnt(56)
	v_lshlrev_b32_e32 v8, 16, v83
	v_and_b32_e32 v9, 0xffff0000, v83
	v_mov_b32_e32 v45, v7
	v_pk_add_f32 v[6:7], v[44:45], v[8:9]
	global_load_dword v76, v[84:85], off
	v_lshl_add_u64 v[84:85], v[84:85], 0, v[88:89]
	global_load_dword v77, v[84:85], off
	v_lshl_add_u64 v[84:85], v[84:85], 0, v[88:89]
	global_load_dword v78, v[84:85], off
	v_lshl_add_u64 v[84:85], v[84:85], 0, v[88:89]
	global_load_dword v79, v[84:85], off
	v_lshl_add_u64 v[84:85], v[84:85], 0, v[88:89]
	global_load_dword v80, v[84:85], off
	v_lshl_add_u64 v[84:85], v[84:85], 0, v[88:89]
	global_load_dword v81, v[84:85], off
	v_lshl_add_u64 v[84:85], v[84:85], 0, v[88:89]
	global_load_dword v82, v[84:85], off
	v_lshl_add_u64 v[84:85], v[84:85], 0, v[88:89]
	global_load_dword v83, v[84:85], off
	v_lshl_add_u64 v[84:85], v[84:85], 0, v[88:89]
	v_cvt_pk_bf16_f32 v46, v6, v7
	global_store_dword v[86:87], v46, off
	v_pk_mul_f32 v[42:43], v[4:5], v[6:7]
	v_lshl_add_u64 v[86:87], v[86:87], 0, v[88:89]
	v_pk_fma_f32 v[44:45], v[2:3], v[6:7], v[42:43] op_sel:[0,0,1] op_sel_hi:[1,1,0] neg_lo:[0,0,1] neg_hi:[0,0,1]
	v_pk_fma_f32 v[6:7], v[2:3], v[6:7], v[42:43] op_sel:[0,0,1] op_sel_hi:[1,1,0]
	s_waitcnt vmcnt(56)
	v_lshlrev_b32_e32 v8, 16, v52
	v_and_b32_e32 v9, 0xffff0000, v52
	v_mov_b32_e32 v45, v7
	v_pk_add_f32 v[6:7], v[44:45], v[8:9]
	v_cvt_pk_bf16_f32 v47, v6, v7
	global_store_dword v[86:87], v47, off
	v_pk_mul_f32 v[42:43], v[4:5], v[6:7]
	v_lshl_add_u64 v[86:87], v[86:87], 0, v[88:89]
	v_pk_fma_f32 v[44:45], v[2:3], v[6:7], v[42:43] op_sel:[0,0,1] op_sel_hi:[1,1,0] neg_lo:[0,0,1] neg_hi:[0,0,1]
	v_pk_fma_f32 v[6:7], v[2:3], v[6:7], v[42:43] op_sel:[0,0,1] op_sel_hi:[1,1,0]
	s_waitcnt vmcnt(56)
	v_lshlrev_b32_e32 v8, 16, v53
	v_and_b32_e32 v9, 0xffff0000, v53
	v_mov_b32_e32 v45, v7
	v_pk_add_f32 v[6:7], v[44:45], v[8:9]
	v_cvt_pk_bf16_f32 v46, v6, v7
	global_store_dword v[86:87], v46, off
	v_pk_mul_f32 v[42:43], v[4:5], v[6:7]
	v_lshl_add_u64 v[86:87], v[86:87], 0, v[88:89]
	v_pk_fma_f32 v[44:45], v[2:3], v[6:7], v[42:43] op_sel:[0,0,1] op_sel_hi:[1,1,0] neg_lo:[0,0,1] neg_hi:[0,0,1]
	v_pk_fma_f32 v[6:7], v[2:3], v[6:7], v[42:43] op_sel:[0,0,1] op_sel_hi:[1,1,0]
	s_waitcnt vmcnt(56)
; DEV unsigned pk_bf16(float lo, float hi) { unsigned r; asm("v_cvt_pk_bf16_f32 %0, %1, %2" : "=v"(r) : "v"(lo), "v"(hi)); return r; }
; DEV float bflo(unsigned w) { return __uint_as_float(w << 16); }
; DEV float bfhi(unsigned w) { return __uint_as_float(w & 0xffff0000u); }
; DEV void ph_carry(const P& p, int l, bool need) {
;     ...
;     for (int blk = 0; blk < 17; ++blk) {
;       unsigned v[8]; int rows[8];
; #pragma unroll
;       for (int e = 0; e < 8; ++e) {
;         int r;
;         if (blk == 0) r = 1024 + b * 8 + (dir ? 7 - e : e);
;         else { const int j = (blk - 1) * 8 + e; r = b * 128 + (dir ? 127 - j : j); }
;         rows[e] = r; v[e] = S[(size_t)r * 4096];
;       }
; #pragma unroll
;       for (int e = 0; e < 8; ++e) {
;         S[(size_t)rows[e] * 4096] = pk_bf16(sr, si);
;         const float nr = at.x * sr - at.y * si + bflo(v[e]), ni = at.x * si + at.y * sr + bfhi(v[e]);
;         sr = nr; si = ni;
;       }
	v_lshlrev_b32_e32 v8, 16, v54
	v_and_b32_e32 v9, 0xffff0000, v54
	v_mov_b32_e32 v45, v7
	v_pk_add_f32 v[6:7], v[44:45], v[8:9]
	v_cvt_pk_bf16_f32 v47, v6, v7
	global_store_dword v[86:87], v47, off
	v_pk_mul_f32 v[42:43], v[4:5], v[6:7]
	v_lshl_add_u64 v[86:87], v[86:87], 0, v[88:89]
	v_pk_fma_f32 v[44:45], v[2:3], v[6:7], v[42:43] op_sel:[0,0,1] op_sel_hi:[1,1,0] neg_lo:[0,0,1] neg_hi:[0,0,1]
	v_pk_fma_f32 v[6:7], v[2:3], v[6:7], v[42:43] op_sel:[0,0,1] op_sel_hi:[1,1,0]
	s_waitcnt vmcnt(56)
	v_lshlrev_b32_e32 v8, 16, v55
	v_and_b32_e32 v9, 0xffff0000, v55
	v_mov_b32_e32 v45, v7
	v_pk_add_f32 v[6:7], v[44:45], v[8:9]
	v_cvt_pk_bf16_f32 v46, v6, v7
	global_store_dword v[86:87], v46, off
	v_pk_mul_f32 v[42:43], v[4:5], v[6:7]
	v_lshl_add_u64 v[86:87], v[86:87], 0, v[88:89]
	v_pk_fma_f32 v[44:45], v[2:3], v[6:7], v[42:43] op_sel:[0,0,1] op_sel_hi:[1,1,0] neg_lo:[0,0,1] neg_hi:[0,0,1]
	v_pk_fma_f32 v[6:7], v[2:3], v[6:7], v[42:43] op_sel:[0,0,1] op_sel_hi:[1,1,0]
	s_waitcnt vmcnt(56)
	v_lshlrev_b32_e32 v8, 16, v56
	v_and_b32_e32 v9, 0xffff0000, v56
	v_mov_b32_e32 v45, v7
	v_pk_add_f32 v[6:7], v[44:45], v[8:9]
	v_cvt_pk_bf16_f32 v47, v6, v7
	global_store_dword v[86:87], v47, off
	v_pk_mul_f32 v[42:43], v[4:5], v[6:7]
	v_lshl_add_u64 v[86:87], v[86:87], 0, v[88:89]
	v_pk_fma_f32 v[44:45], v[2:3], v[6:7], v[42:43] op_sel:[0,0,1] op_sel_hi:[1,1,0] neg_lo:[0,0,1] neg_hi:[0,0,1]
	v_pk_fma_f32 v[6:7], v[2:3], v[6:7], v[42:43] op_sel:[0,0,1] op_sel_hi:[1,1,0]
	s_waitcnt vmcnt(56)
	v_lshlrev_b32_e32 v8, 16, v57
	v_and_b32_e32 v9, 0xffff0000, v57
	v_mov_b32_e32 v45, v7
	v_pk_add_f32 v[6:7], v[44:45], v[8:9]
	v_cvt_pk_bf16_f32 v46, v6, v7
	global_store_dword v[86:87], v46, off
	v_pk_mul_f32 v[42:43], v[4:5], v[6:7]
	v_lshl_add_u64 v[86:87], v[86:87], 0, v[88:89]
	v_pk_fma_f32 v[44:45], v[2:3], v[6:7], v[42:43] op_sel:[0,0,1] op_sel_hi:[1,1,0] neg_lo:[0,0,1] neg_hi:[0,0,1]
	v_pk_fma_f32 v[6:7], v[2:3], v[6:7], v[42:43] op_sel:[0,0,1] op_sel_hi:[1,1,0]
	s_waitcnt vmcnt(56)
	v_lshlrev_b32_e32 v8, 16, v58
	v_and_b32_e32 v9, 0xffff0000, v58
	v_mov_b32_e32 v45, v7
	v_pk_add_f32 v[6:7], v[44:45], v[8:9]
	v_cvt_pk_bf16_f32 v47, v6, v7
	global_store_dword v[86:87], v47, off
	v_pk_mul_f32 v[42:43], v[4:5], v[6:7]
	v_lshl_add_u64 v[86:87], v[86:87], 0, v[88:89]
	v_pk_fma_f32 v[44:45], v[2:3], v[6:7], v[42:43] op_sel:[0,0,1] op_sel_hi:[1,1,0] neg_lo:[0,0,1] neg_hi:[0,0,1]
	v_pk_fma_f32 v[6:7], v[2:3], v[6:7], v[42:43] op_sel:[0,0,1] op_sel_hi:[1,1,0]
	s_waitcnt vmcnt(56)
	v_lshlrev_b32_e32 v8, 16, v59
	v_and_b32_e32 v9, 0xffff0000, v59
	v_mov_b32_e32 v45, v7
	v_pk_add_f32 v[6:7], v[44:45], v[8:9]
	v_cvt_pk_bf16_f32 v46, v6, v7
	global_store_dword v[86:87], v46, off
	v_pk_mul_f32 v[42:43], v[4:5], v[6:7]
	v_lshl_add_u64 v[86:87], v[86:87], 0, v[88:89]
	v_pk_fma_f32 v[44:45], v[2:3], v[6:7], v[42:43] op_sel:[0,0,1] op_sel_hi:[1,1,0] neg_lo:[0,0,1] neg_hi:[0,0,1]
	v_pk_fma_f32 v[6:7], v[2:3], v[6:7], v[42:43] op_sel:[0,0,1] op_sel_hi:[1,1,0]
	s_waitcnt vmcnt(48)
	v_lshlrev_b32_e32 v8, 16, v60
	v_and_b32_e32 v9, 0xffff0000, v60
	v_mov_b32_e32 v45, v7
	v_pk_add_f32 v[6:7], v[44:45], v[8:9]
	v_cvt_pk_bf16_f32 v47, v6, v7
	global_store_dword v[86:87], v47, off
	v_pk_mul_f32 v[42:43], v[4:5], v[6:7]
	v_lshl_add_u64 v[86:87], v[86:87], 0, v[88:89]
	v_pk_fma_f32 v[44:45], v[2:3], v[6:7], v[42:43] op_sel:[0,0,1] op_sel_hi:[1,1,0] neg_lo:[0,0,1] neg_hi:[0,0,1]
	v_pk_fma_f32 v[6:7], v[2:3], v[6:7], v[42:43] op_sel:[0,0,1] op_sel_hi:[1,1,0]
	s_waitcnt vmcnt(48)
	v_lshlrev_b32_e32 v8, 16, v61
	v_and_b32_e32 v9, 0xffff0000, v61
	v_mov_b32_e32 v45, v7
	v_pk_add_f32 v[6:7], v[44:45], v[8:9]
	v_cvt_pk_bf16_f32 v46, v6, v7
	global_store_dword v[86:87], v46, off
	v_pk_mul_f32 v[42:43], v[4:5], v[6:7]
	v_lshl_add_u64 v[86:87], v[86:87], 0, v[88:89]
	v_pk_fma_f32 v[44:45], v[2:3], v[6:7], v[42:43] op_sel:[0,0,1] op_sel_hi:[1,1,0] neg_lo:[0,0,1] neg_hi:[0,0,1]
	v_pk_fma_f32 v[6:7], v[2:3], v[6:7], v[42:43] op_sel:[0,0,1] op_sel_hi:[1,1,0]
	s_waitcnt vmcnt(48)
	v_lshlrev_b32_e32 v8, 16, v62
	v_and_b32_e32 v9, 0xffff0000, v62
	v_mov_b32_e32 v45, v7
	v_pk_add_f32 v[6:7], v[44:45], v[8:9]
	v_cvt_pk_bf16_f32 v47, v6, v7
	global_store_dword v[86:87], v47, off
	v_pk_mul_f32 v[42:43], v[4:5], v[6:7]
	v_lshl_add_u64 v[86:87], v[86:87], 0, v[88:89]
	v_pk_fma_f32 v[44:45], v[2:3], v[6:7], v[42:43] op_sel:[0,0,1] op_sel_hi:[1,1,0] neg_lo:[0,0,1] neg_hi:[0,0,1]
	v_pk_fma_f32 v[6:7], v[2:3], v[6:7], v[42:43] op_sel:[0,0,1] op_sel_hi:[1,1,0]
	s_waitcnt vmcnt(48)
	v_lshlrev_b32_e32 v8, 16, v63
	v_and_b32_e32 v9, 0xffff0000, v63
	v_mov_b32_e32 v45, v7
	v_pk_add_f32 v[6:7], v[44:45], v[8:9]
	v_cvt_pk_bf16_f32 v46, v6, v7
	global_store_dword v[86:87], v46, off
	v_pk_mul_f32 v[42:43], v[4:5], v[6:7]
	v_lshl_add_u64 v[86:87], v[86:87], 0, v[88:89]
	v_pk_fma_f32 v[44:45], v[2:3], v[6:7], v[42:43] op_sel:[0,0,1] op_sel_hi:[1,1,0] neg_lo:[0,0,1] neg_hi:[0,0,1]
	v_pk_fma_f32 v[6:7], v[2:3], v[6:7], v[42:43] op_sel:[0,0,1] op_sel_hi:[1,1,0]
	s_waitcnt vmcnt(48)
	v_lshlrev_b32_e32 v8, 16, v64
	v_and_b32_e32 v9, 0xffff0000, v64
	v_mov_b32_e32 v45, v7
	v_pk_add_f32 v[6:7], v[44:45], v[8:9]
	v_cvt_pk_bf16_f32 v47, v6, v7
	global_store_dword v[86:87], v47, off
	v_pk_mul_f32 v[42:43], v[4:5], v[6:7]
	v_lshl_add_u64 v[86:87], v[86:87], 0, v[88:89]
	v_pk_fma_f32 v[44:45], v[2:3], v[6:7], v[42:43] op_sel:[0,0,1] op_sel_hi:[1,1,0] neg_lo:[0,0,1] neg_hi:[0,0,1]
	v_pk_fma_f32 v[6:7], v[2:3], v[6:7], v[42:43] op_sel:[0,0,1] op_sel_hi:[1,1,0]
	s_waitcnt vmcnt(48)
; DEV unsigned pk_bf16(float lo, float hi) { unsigned r; asm("v_cvt_pk_bf16_f32 %0, %1, %2" : "=v"(r) : "v"(lo), "v"(hi)); return r; }
; DEV float bflo(unsigned w) { return __uint_as_float(w << 16); }
; DEV float bfhi(unsigned w) { return __uint_as_float(w & 0xffff0000u); }
; DEV void ph_carry(const P& p, int l, bool need) {
;     ...
;     for (int blk = 0; blk < 17; ++blk) {
;       unsigned v[8]; int rows[8];
; #pragma unroll
;       for (int e = 0; e < 8; ++e) {
;         int r;
;         if (blk == 0) r = 1024 + b * 8 + (dir ? 7 - e : e);
;         else { const int j = (blk - 1) * 8 + e; r = b * 128 + (dir ? 127 - j : j); }
;         rows[e] = r; v[e] = S[(size_t)r * 4096];
;       }
; #pragma unroll
;       for (int e = 0; e < 8; ++e) {
;         S[(size_t)rows[e] * 4096] = pk_bf16(sr, si);
;         const float nr = at.x * sr - at.y * si + bflo(v[e]), ni = at.x * si + at.y * sr + bfhi(v[e]);
;         sr = nr; si = ni;
;       }
;     }
	v_lshlrev_b32_e32 v8, 16, v65
	v_and_b32_e32 v9, 0xffff0000, v65
	v_mov_b32_e32 v45, v7
	v_pk_add_f32 v[6:7], v[44:45], v[8:9]
	v_cvt_pk_bf16_f32 v46, v6, v7
	global_store_dword v[86:87], v46, off
	v_pk_mul_f32 v[42:43], v[4:5], v[6:7]
	v_lshl_add_u64 v[86:87], v[86:87], 0, v[88:89]
	v_pk_fma_f32 v[44:45], v[2:3], v[6:7], v[42:43] op_sel:[0,0,1] op_sel_hi:[1,1,0] neg_lo:[0,0,1] neg_hi:[0,0,1]
	v_pk_fma_f32 v[6:7], v[2:3], v[6:7], v[42:43] op_sel:[0,0,1] op_sel_hi:[1,1,0]
	s_waitcnt vmcnt(48)
	v_lshlrev_b32_e32 v8, 16, v66
	v_and_b32_e32 v9, 0xffff0000, v66
	v_mov_b32_e32 v45, v7
	v_pk_add_f32 v[6:7], v[44:45], v[8:9]
	v_cvt_pk_bf16_f32 v47, v6, v7
	global_store_dword v[86:87], v47, off
	v_pk_mul_f32 v[42:43], v[4:5], v[6:7]
	v_lshl_add_u64 v[86:87], v[86:87], 0, v[88:89]
	v_pk_fma_f32 v[44:45], v[2:3], v[6:7], v[42:43] op_sel:[0,0,1] op_sel_hi:[1,1,0] neg_lo:[0,0,1] neg_hi:[0,0,1]
	v_pk_fma_f32 v[6:7], v[2:3], v[6:7], v[42:43] op_sel:[0,0,1] op_sel_hi:[1,1,0]
	s_waitcnt vmcnt(48)
	v_lshlrev_b32_e32 v8, 16, v67
	v_and_b32_e32 v9, 0xffff0000, v67
	v_mov_b32_e32 v45, v7
	v_pk_add_f32 v[6:7], v[44:45], v[8:9]
	v_cvt_pk_bf16_f32 v46, v6, v7
	global_store_dword v[86:87], v46, off
	v_pk_mul_f32 v[42:43], v[4:5], v[6:7]
	v_lshl_add_u64 v[86:87], v[86:87], 0, v[88:89]
	v_pk_fma_f32 v[44:45], v[2:3], v[6:7], v[42:43] op_sel:[0,0,1] op_sel_hi:[1,1,0] neg_lo:[0,0,1] neg_hi:[0,0,1]
	v_pk_fma_f32 v[6:7], v[2:3], v[6:7], v[42:43] op_sel:[0,0,1] op_sel_hi:[1,1,0]
	s_waitcnt vmcnt(40)
	v_lshlrev_b32_e32 v8, 16, v68
	v_and_b32_e32 v9, 0xffff0000, v68
	v_mov_b32_e32 v45, v7
	v_pk_add_f32 v[6:7], v[44:45], v[8:9]
	v_cvt_pk_bf16_f32 v47, v6, v7
	global_store_dword v[86:87], v47, off
	v_pk_mul_f32 v[42:43], v[4:5], v[6:7]
	v_lshl_add_u64 v[86:87], v[86:87], 0, v[88:89]
	v_pk_fma_f32 v[44:45], v[2:3], v[6:7], v[42:43] op_sel:[0,0,1] op_sel_hi:[1,1,0] neg_lo:[0,0,1] neg_hi:[0,0,1]
	v_pk_fma_f32 v[6:7], v[2:3], v[6:7], v[42:43] op_sel:[0,0,1] op_sel_hi:[1,1,0]
	s_waitcnt vmcnt(40)
	v_lshlrev_b32_e32 v8, 16, v69
	v_and_b32_e32 v9, 0xffff0000, v69
	v_mov_b32_e32 v45, v7
	v_pk_add_f32 v[6:7], v[44:45], v[8:9]
	v_cvt_pk_bf16_f32 v46, v6, v7
	global_store_dword v[86:87], v46, off
	v_pk_mul_f32 v[42:43], v[4:5], v[6:7]
	v_lshl_add_u64 v[86:87], v[86:87], 0, v[88:89]
	v_pk_fma_f32 v[44:45], v[2:3], v[6:7], v[42:43] op_sel:[0,0,1] op_sel_hi:[1,1,0] neg_lo:[0,0,1] neg_hi:[0,0,1]
	v_pk_fma_f32 v[6:7], v[2:3], v[6:7], v[42:43] op_sel:[0,0,1] op_sel_hi:[1,1,0]
	s_waitcnt vmcnt(40)
	v_lshlrev_b32_e32 v8, 16, v70
	v_and_b32_e32 v9, 0xffff0000, v70
	v_mov_b32_e32 v45, v7
	v_pk_add_f32 v[6:7], v[44:45], v[8:9]
	v_cvt_pk_bf16_f32 v47, v6, v7
	global_store_dword v[86:87], v47, off
	v_pk_mul_f32 v[42:43], v[4:5], v[6:7]
	v_lshl_add_u64 v[86:87], v[86:87], 0, v[88:89]
	v_pk_fma_f32 v[44:45], v[2:3], v[6:7], v[42:43] op_sel:[0,0,1] op_sel_hi:[1,1,0] neg_lo:[0,0,1] neg_hi:[0,0,1]
	v_pk_fma_f32 v[6:7], v[2:3], v[6:7], v[42:43] op_sel:[0,0,1] op_sel_hi:[1,1,0]
	s_waitcnt vmcnt(40)
	v_lshlrev_b32_e32 v8, 16, v71
	v_and_b32_e32 v9, 0xffff0000, v71
	v_mov_b32_e32 v45, v7
	v_pk_add_f32 v[6:7], v[44:45], v[8:9]
	v_cvt_pk_bf16_f32 v46, v6, v7
	global_store_dword v[86:87], v46, off
	v_pk_mul_f32 v[42:43], v[4:5], v[6:7]
	v_lshl_add_u64 v[86:87], v[86:87], 0, v[88:89]
	v_pk_fma_f32 v[44:45], v[2:3], v[6:7], v[42:43] op_sel:[0,0,1] op_sel_hi:[1,1,0] neg_lo:[0,0,1] neg_hi:[0,0,1]
	v_pk_fma_f32 v[6:7], v[2:3], v[6:7], v[42:43] op_sel:[0,0,1] op_sel_hi:[1,1,0]
	s_waitcnt vmcnt(40)
	v_lshlrev_b32_e32 v8, 16, v72
	v_and_b32_e32 v9, 0xffff0000, v72
	v_mov_b32_e32 v45, v7
	v_pk_add_f32 v[6:7], v[44:45], v[8:9]
	v_cvt_pk_bf16_f32 v47, v6, v7
	global_store_dword v[86:87], v47, off
	v_pk_mul_f32 v[42:43], v[4:5], v[6:7]
	v_lshl_add_u64 v[86:87], v[86:87], 0, v[88:89]
	v_pk_fma_f32 v[44:45], v[2:3], v[6:7], v[42:43] op_sel:[0,0,1] op_sel_hi:[1,1,0] neg_lo:[0,0,1] neg_hi:[0,0,1]
	v_pk_fma_f32 v[6:7], v[2:3], v[6:7], v[42:43] op_sel:[0,0,1] op_sel_hi:[1,1,0]
	s_waitcnt vmcnt(40)
	v_lshlrev_b32_e32 v8, 16, v73
	v_and_b32_e32 v9, 0xffff0000, v73
	v_mov_b32_e32 v45, v7
	v_pk_add_f32 v[6:7], v[44:45], v[8:9]
	v_cvt_pk_bf16_f32 v46, v6, v7
	global_store_dword v[86:87], v46, off
	v_pk_mul_f32 v[42:43], v[4:5], v[6:7]
	v_lshl_add_u64 v[86:87], v[86:87], 0, v[88:89]
	v_pk_fma_f32 v[44:45], v[2:3], v[6:7], v[42:43] op_sel:[0,0,1] op_sel_hi:[1,1,0] neg_lo:[0,0,1] neg_hi:[0,0,1]
	v_pk_fma_f32 v[6:7], v[2:3], v[6:7], v[42:43] op_sel:[0,0,1] op_sel_hi:[1,1,0]
	s_waitcnt vmcnt(40)
; DEV int vbid() { return (int)blockIdx.x * 2 + vbsel(); }
; DEV int vgrid() { return (int)gridDim.x * 2; }
; DEV unsigned pk_bf16(float lo, float hi) { unsigned r; asm("v_cvt_pk_bf16_f32 %0, %1, %2" : "=v"(r) : "v"(lo), "v"(hi)); return r; }
; DEV float bflo(unsigned w) { return __uint_as_float(w << 16); }
; DEV float bfhi(unsigned w) { return __uint_as_float(w & 0xffff0000u); }
; DEV void ph_carry(const P& p, int l, bool need) {
;     ...
;   for (int it = vbid(); it < 128; it += vgrid()) {
;     const int idx = it * 256 + tid, pp = idx & 63, dir = (idx >> 6) & 1, g = (idx >> 7) & 31, b = idx >> 12;
;     const Disc d = s5_disc(p, l, dir, g, pp);
;     const float2 at = cpow(d, 32);
;     unsigned* S = (unsigned*)(p.ws + OFF_S) + (g * 256 + dir * 128 + pp * 2) / 2;
;     float sr = 0.f, si = 0.f;
;     for (int blk = 0; blk < 17; ++blk) {
;       unsigned v[8]; int rows[8];
; #pragma unroll
;       for (int e = 0; e < 8; ++e) {
;         int r;
;         if (blk == 0) r = 1024 + b * 8 + (dir ? 7 - e : e);
;         else { const int j = (blk - 1) * 8 + e; r = b * 128 + (dir ? 127 - j : j); }
;         rows[e] = r; v[e] = S[(size_t)r * 4096];
;       }
; #pragma unroll
;       for (int e = 0; e < 8; ++e) {
;         S[(size_t)rows[e] * 4096] = pk_bf16(sr, si);
;         const float nr = at.x * sr - at.y * si + bflo(v[e]), ni = at.x * si + at.y * sr + bfhi(v[e]);
;         sr = nr; si = ni;
;       }
;     }
	v_lshlrev_b32_e32 v8, 16, v74
	v_and_b32_e32 v9, 0xffff0000, v74
	v_mov_b32_e32 v45, v7
	v_pk_add_f32 v[6:7], v[44:45], v[8:9]
	v_cvt_pk_bf16_f32 v47, v6, v7
	global_store_dword v[86:87], v47, off
	v_pk_mul_f32 v[42:43], v[4:5], v[6:7]
	v_lshl_add_u64 v[86:87], v[86:87], 0, v[88:89]
	v_pk_fma_f32 v[44:45], v[2:3], v[6:7], v[42:43] op_sel:[0,0,1] op_sel_hi:[1,1,0] neg_lo:[0,0,1] neg_hi:[0,0,1]
	v_pk_fma_f32 v[6:7], v[2:3], v[6:7], v[42:43] op_sel:[0,0,1] op_sel_hi:[1,1,0]
	s_waitcnt vmcnt(40)
	v_lshlrev_b32_e32 v8, 16, v75
	v_and_b32_e32 v9, 0xffff0000, v75
	v_mov_b32_e32 v45, v7
	v_pk_add_f32 v[6:7], v[44:45], v[8:9]
	v_cvt_pk_bf16_f32 v46, v6, v7
	global_store_dword v[86:87], v46, off
	v_pk_mul_f32 v[42:43], v[4:5], v[6:7]
	v_lshl_add_u64 v[86:87], v[86:87], 0, v[88:89]
	v_pk_fma_f32 v[44:45], v[2:3], v[6:7], v[42:43] op_sel:[0,0,1] op_sel_hi:[1,1,0] neg_lo:[0,0,1] neg_hi:[0,0,1]
	v_pk_fma_f32 v[6:7], v[2:3], v[6:7], v[42:43] op_sel:[0,0,1] op_sel_hi:[1,1,0]
	s_waitcnt vmcnt(32)
	v_lshlrev_b32_e32 v8, 16, v76
	v_and_b32_e32 v9, 0xffff0000, v76
	v_mov_b32_e32 v45, v7
	v_pk_add_f32 v[6:7], v[44:45], v[8:9]
	v_cvt_pk_bf16_f32 v47, v6, v7
	global_store_dword v[86:87], v47, off
	v_pk_mul_f32 v[42:43], v[4:5], v[6:7]
	v_lshl_add_u64 v[86:87], v[86:87], 0, v[88:89]
	v_pk_fma_f32 v[44:45], v[2:3], v[6:7], v[42:43] op_sel:[0,0,1] op_sel_hi:[1,1,0] neg_lo:[0,0,1] neg_hi:[0,0,1]
	v_pk_fma_f32 v[6:7], v[2:3], v[6:7], v[42:43] op_sel:[0,0,1] op_sel_hi:[1,1,0]
	s_waitcnt vmcnt(32)
	v_lshlrev_b32_e32 v8, 16, v77
	v_and_b32_e32 v9, 0xffff0000, v77
	v_mov_b32_e32 v45, v7
	v_pk_add_f32 v[6:7], v[44:45], v[8:9]
	v_cvt_pk_bf16_f32 v46, v6, v7
	global_store_dword v[86:87], v46, off
	v_pk_mul_f32 v[42:43], v[4:5], v[6:7]
	v_lshl_add_u64 v[86:87], v[86:87], 0, v[88:89]
	v_pk_fma_f32 v[44:45], v[2:3], v[6:7], v[42:43] op_sel:[0,0,1] op_sel_hi:[1,1,0] neg_lo:[0,0,1] neg_hi:[0,0,1]
	v_pk_fma_f32 v[6:7], v[2:3], v[6:7], v[42:43] op_sel:[0,0,1] op_sel_hi:[1,1,0]
	s_waitcnt vmcnt(32)
	v_lshlrev_b32_e32 v8, 16, v78
	v_and_b32_e32 v9, 0xffff0000, v78
	v_mov_b32_e32 v45, v7
	v_pk_add_f32 v[6:7], v[44:45], v[8:9]
	v_cvt_pk_bf16_f32 v47, v6, v7
	global_store_dword v[86:87], v47, off
	v_pk_mul_f32 v[42:43], v[4:5], v[6:7]
	v_lshl_add_u64 v[86:87], v[86:87], 0, v[88:89]
	v_pk_fma_f32 v[44:45], v[2:3], v[6:7], v[42:43] op_sel:[0,0,1] op_sel_hi:[1,1,0] neg_lo:[0,0,1] neg_hi:[0,0,1]
	v_pk_fma_f32 v[6:7], v[2:3], v[6:7], v[42:43] op_sel:[0,0,1] op_sel_hi:[1,1,0]
	s_waitcnt vmcnt(32)
	v_lshlrev_b32_e32 v8, 16, v79
	v_and_b32_e32 v9, 0xffff0000, v79
	v_mov_b32_e32 v45, v7
	v_pk_add_f32 v[6:7], v[44:45], v[8:9]
	v_cvt_pk_bf16_f32 v46, v6, v7
	global_store_dword v[86:87], v46, off
	v_pk_mul_f32 v[42:43], v[4:5], v[6:7]
	v_lshl_add_u64 v[86:87], v[86:87], 0, v[88:89]
	v_pk_fma_f32 v[44:45], v[2:3], v[6:7], v[42:43] op_sel:[0,0,1] op_sel_hi:[1,1,0] neg_lo:[0,0,1] neg_hi:[0,0,1]
	v_pk_fma_f32 v[6:7], v[2:3], v[6:7], v[42:43] op_sel:[0,0,1] op_sel_hi:[1,1,0]
	s_waitcnt vmcnt(32)
	v_lshlrev_b32_e32 v8, 16, v80
	v_and_b32_e32 v9, 0xffff0000, v80
	v_mov_b32_e32 v45, v7
	v_pk_add_f32 v[6:7], v[44:45], v[8:9]
	v_cvt_pk_bf16_f32 v47, v6, v7
	global_store_dword v[86:87], v47, off
	v_pk_mul_f32 v[42:43], v[4:5], v[6:7]
	v_lshl_add_u64 v[86:87], v[86:87], 0, v[88:89]
	v_pk_fma_f32 v[44:45], v[2:3], v[6:7], v[42:43] op_sel:[0,0,1] op_sel_hi:[1,1,0] neg_lo:[0,0,1] neg_hi:[0,0,1]
	v_pk_fma_f32 v[6:7], v[2:3], v[6:7], v[42:43] op_sel:[0,0,1] op_sel_hi:[1,1,0]
	s_waitcnt vmcnt(32)
	v_lshlrev_b32_e32 v8, 16, v81
	v_and_b32_e32 v9, 0xffff0000, v81
	v_mov_b32_e32 v45, v7
	v_pk_add_f32 v[6:7], v[44:45], v[8:9]
	v_cvt_pk_bf16_f32 v46, v6, v7
	global_store_dword v[86:87], v46, off
	v_pk_mul_f32 v[42:43], v[4:5], v[6:7]
	v_lshl_add_u64 v[86:87], v[86:87], 0, v[88:89]
	v_pk_fma_f32 v[44:45], v[2:3], v[6:7], v[42:43] op_sel:[0,0,1] op_sel_hi:[1,1,0] neg_lo:[0,0,1] neg_hi:[0,0,1]
	v_pk_fma_f32 v[6:7], v[2:3], v[6:7], v[42:43] op_sel:[0,0,1] op_sel_hi:[1,1,0]
	s_waitcnt vmcnt(32)
	v_lshlrev_b32_e32 v8, 16, v82
	v_and_b32_e32 v9, 0xffff0000, v82
	v_mov_b32_e32 v45, v7
	v_pk_add_f32 v[6:7], v[44:45], v[8:9]
	v_cvt_pk_bf16_f32 v47, v6, v7
	global_store_dword v[86:87], v47, off
	v_pk_mul_f32 v[42:43], v[4:5], v[6:7]
	v_lshl_add_u64 v[86:87], v[86:87], 0, v[88:89]
	v_pk_fma_f32 v[44:45], v[2:3], v[6:7], v[42:43] op_sel:[0,0,1] op_sel_hi:[1,1,0] neg_lo:[0,0,1] neg_hi:[0,0,1]
	v_pk_fma_f32 v[6:7], v[2:3], v[6:7], v[42:43] op_sel:[0,0,1] op_sel_hi:[1,1,0]
	s_waitcnt vmcnt(32)
	v_lshlrev_b32_e32 v8, 16, v83
	v_and_b32_e32 v9, 0xffff0000, v83
	v_mov_b32_e32 v45, v7
	v_pk_add_f32 v[6:7], v[44:45], v[8:9]
	s_add_i32 s10, s10, s91
	s_cmpk_gt_i32 s10, 0x7f
	s_cbranch_scc0 .LBB0_305
